# head-major P layout for mixer A (GEMM_IN epilogue address patch + attn_a), XCD-aware unit map
# speedup vs baseline: 1.3195x; 1.0114x over previous
; #define PG8_LAS __attribute__((address_space(3)))
; DI unsigned xb_add(unsigned* p, unsigned v) { return __hip_atomic_fetch_add(p, v, __ATOMIC_RELAXED, __HIP_MEMORY_SCOPE_AGENT); }
; DI unsigned xb_xcc_id() { return (unsigned)__builtin_amdgcn_s_getreg((3 << 11) | 20) & 0xFu; }
;     __host__ __device__ bool next(int i, Unit& u) const {
;         const long L = (long)i * G + c; if (L >= nwg) return false;
;         int wgid = (int)L; { const int q = nwg / NXCD, r = nwg % NXCD, xcd = wgid % NXCD, off = wgid / NXCD; wgid = (xcd < r ? xcd * (q + 1) : r * (q + 1) + (xcd - r) * q) + off; }
;         const int nig = WGM * nN, gid = wgid / nig, fm = gid * WGM, gsz = (nM - fm) < WGM ? (nM - fm) : WGM;
;         u.pm = fm + ((wgid % nig) % gsz); u.pn = (wgid % nig) / gsz; return true;
; __global__ void __launch_bounds__(512, 2) mega(Params pp) {
;   extern __shared__ __attribute__((aligned(16))) char smem0[];
;   cg::grid_group grid = cg::this_grid();
;   const int wv8_ = __builtin_amdgcn_readfirstlane((int)threadIdx.x >> 6);
;   const int hb_ = wv8_ >> 2, wv_ = wv8_ & 3;
;   const int vb_ = (int)blockIdx.x * 2 + hb_, nvb_ = (int)gridDim.x * 2;
;   {
;     volatile PG8_LAS unsigned* st = (volatile PG8_LAS unsigned*)(smem0 + 2 * HALF_LDS);
;     const bool lead0 = tidx(wv8_) == 0;
;     if (lead0) { st[0] = 0u; st[1] = 0u; (void)xb_add(&((unsigned*)(pp.c.ws + WS_BAR))[XB_XCNT(xb_xcc_id())], 1u); }
;     __syncthreads();
;   }
;   if (pp.ph1 < 0) grid.sync();
; #pragma unroll 1
;   for (int ph = pp.ph0; ph < pp.ph1; ++ph) {
;     const Ctx& p = pp.c;
;     size_t wsoff_ = 0; asm volatile("" : "+s"(wsoff_));
;     char* ws_ = pp.c.ws + wsoff_;
;     unsigned smoff_ = 0; asm volatile("" : "+v"(smoff_));
;     char* smem = smem0 + hb_ * HALF_LDS + smoff_;
;     const u16* WT = (const u16*)(ws_ + WS_WT);
;     u16* H = (u16*)(ws_ + WS_H);
;     u16* Pm = (u16*)(ws_ + WS_P);
;     const int code = pp.ops[ph];
;     const int op = code & 15, l = (code >> 4) & 3, half = (code >> 6) & 1;
;     const int kind = l % 3, j = l / 3;
;     const float* xcur = (code >> 7) ? p.x : p.out;
;     switch (op) {
.LBB0_16:
	v_readlane_b32 s2, v252, 0
	s_lshr_b32 s0, s1, 8
	s_and_b32 s33, s2, 3
	s_lshl_b32 s2, s16, 1
	s_add_i32 s34, s0, s2
	s_mul_i32 s2, s0, 0x12c00
	s_lshl_b32 s52, s17, 1
	s_add_i32 s37, s2, 0
	s_cmpk_lt_i32 s16, 0x800
	s_cselect_b64 s[2:3], -1, 0
	v_writelane_b32 v252, s2, 2
	s_ashr_i32 s36, s16, 31
	s_ashr_i32 s53, s52, 31
	v_writelane_b32 v252, s3, 3
	s_lshr_b32 s2, s36, 29
	s_add_i32 s2, s16, s2
	s_ashr_i32 s20, s2, 3
	s_and_b32 s2, s2, -8
	s_sub_i32 s14, s16, s2
	s_ashr_i32 s35, s34, 31
	s_lshl_b32 s21, s14, 8
	s_ashr_i32 s42, s17, 31
	s_lshl_b32 s2, s34, 5
	s_lshl_b32 s44, s17, 6
	s_lshl_b64 s[40:41], s[52:53], 8
	s_lshl_b64 s[38:39], s[34:35], 8
	s_cmp_gt_i32 s16, 63
	v_writelane_b32 v252, s2, 4
	s_cselect_b64 s[2:3], -1, 0
	v_writelane_b32 v252, s2, 5
	s_movk_i32 s24, 0x89
	s_mov_b32 s85, 0
	v_writelane_b32 v252, s3, 6
	s_sub_i32 s2, s17, 64
	s_sub_i32 s3, s16, 64
	s_cmp_gt_i32 s17, 64
	s_cselect_b32 s3, s3, s16
	s_cselect_b32 s5, s2, s17
	s_cmpk_lt_u32 s3, 0x440
	s_cselect_b64 s[6:7], -1, 0
	v_writelane_b32 v252, s6, 7
	s_and_b32 s2, s3, 7
	s_mulk_i32 s2, 0x88
	v_writelane_b32 v252, s7, 8
	v_writelane_b32 v252, s3, 9
	s_lshr_b32 s3, s3, 3
	s_add_i32 s2, s2, s3
	s_and_b32 s13, s2, 0xffff
	s_mul_i32 s13, s13, 0xf0f1
	s_lshr_b32 s3, s13, 23
	s_lshl_b32 s4, s3, 3
	s_mulk_i32 s3, 0x88
	s_sub_i32 s2, s2, s3
	s_and_b32 s3, s2, 7
	s_or_b32 s3, s4, s3
	s_and_b32 s30, s3, 0xfff
	s_bfe_u32 s3, s2, 0xd0003
	v_writelane_b32 v252, s3, 10
	s_lshr_b32 s18, s2, 3
	v_writelane_b32 v252, s5, 11
	s_ashr_i32 s2, s5, 31
	v_writelane_b32 v252, s2, 12
	s_ashr_i32 s2, s34, 1
	s_cmp_lt_i32 s2, 64
	s_cselect_b64 s[4:5], -1, 0
	s_and_b32 s1, s1, 0x100
	s_cmp_eq_u32 s1, 0
	s_cselect_b64 s[6:7], -1, 0
	s_cmp_lg_u32 s1, 0
	s_cselect_b64 s[8:9], -1, 0
	s_and_b64 s[8:9], s[8:9], s[4:5]
	v_writelane_b32 v252, s8, 13
	s_and_b64 s[4:5], s[6:7], s[4:5]
	s_lshl_b32 s1, s2, 2
	v_writelane_b32 v252, s9, 14
	v_writelane_b32 v252, s4, 15
	s_ashr_i32 s3, s2, 31
	s_lshl_b64 s[6:7], s[2:3], 18
	v_writelane_b32 v252, s5, 16
	s_ashr_i32 s4, s34, 4
	s_ashr_i32 s5, s4, 31
	v_writelane_b32 v252, s1, 17
	s_lshl_b64 s[68:69], s[2:3], 5
	s_lshl_b64 s[4:5], s[4:5], 23
	s_add_i32 s19, s52, 0x7ff
	v_writelane_b32 v252, s6, 18
	s_cmp_lt_i32 s34, 0x8000
	v_mov_b32_e32 v206, 0x358637bd
	v_writelane_b32 v252, s7, 19
	s_cselect_b64 s[6:7], -1, 0
	s_add_i32 s15, s52, 0xfff
	v_writelane_b32 v252, s6, 20
	s_cmpk_lt_i32 s16, 0x200
	v_mov_b32_e32 v207, 0xff800000
	v_writelane_b32 v252, s7, 21
	s_cselect_b64 s[6:7], -1, 0
	v_writelane_b32 v252, s6, 22
	s_add_i32 s12, s52, 0x17ff
	v_mov_b32_e32 v208, 1
	v_writelane_b32 v252, s7, 23
	s_lshl_b32 s6, s14, 6
	s_cmpk_lt_i32 s16, 0x480
	s_cselect_b64 s[8:9], -1, 0
	s_lshr_b32 s1, s14, 31
	s_or_b32 s1, s1, 0x90
	s_mul_i32 s1, s1, s14
	s_add_i32 s1, s1, s20
	v_writelane_b32 v252, s8, 24
	s_mul_hi_i32 s7, s1, 0x38e38e39
	v_mov_b32_e32 v210, 0x3e000000
	v_writelane_b32 v252, s9, 25
	s_lshr_b32 s8, s7, 31
	s_ashr_i32 s7, s7, 4
	s_add_i32 s7, s7, s8
	s_lshl_b32 s9, s7, 3
	s_sub_i32 s8, 0x80, s9
	s_mulk_i32 s7, 0x48
	s_min_u32 s10, s8, 8
	s_sub_i32 s11, s1, s7
	s_cmpk_lt_i32 s16, 0x900
	s_mul_i32 s7, s14, 0x90
	s_cselect_b64 s[22:23], -1, 0
	s_add_i32 s8, s1, s7
	s_mul_hi_i32 s1, s8, 0x38e38e39
	v_writelane_b32 v252, s22, 26
	s_lshr_b32 s7, s1, 31
	s_ashr_i32 s1, s1, 5
	v_writelane_b32 v252, s23, 27
	s_add_i32 s22, s1, s7
	s_lshl_b32 s1, s22, 3
	s_sub_i32 s7, 0x80, s1
	s_mulk_i32 s22, 0x90
	s_min_u32 s7, s7, 8
	s_sub_i32 s8, s8, s22
	s_cmpk_lt_i32 s16, 0x440
	s_cselect_b64 s[22:23], -1, 0
	s_cmp_lt_i32 s14, 0
	v_writelane_b32 v252, s22, 28
	s_cselect_b32 s24, s24, 0x88
	v_cvt_f32_ubyte0_e32 v1, s10
	v_writelane_b32 v252, s23, 29
	s_mul_i32 s22, s14, 0x101
	s_mul_i32 s23, s14, 0x41
	s_mul_i32 s14, s24, s14
	s_cselect_b32 s21, s22, s21
	s_cselect_b32 s22, s23, s6
	s_add_i32 s14, s14, s20
	s_mul_hi_i32 s6, s14, 0x78787879
	s_lshr_b32 s23, s6, 31
	s_ashr_i32 s6, s6, 6
	s_add_i32 s6, s6, s23
	s_mul_i32 s23, s6, 0x88
	s_sub_i32 s14, s14, s23
	s_lshl_b32 s24, s6, 3
	s_bfe_u32 s6, s14, 0x3001c
	s_add_i32 s23, s14, s6
	s_sext_i32_i16 s25, s23
	s_and_b32 s23, s23, 0xfff8
	s_sub_i32 s14, s14, s23
	s_sext_i32_i16 s23, s14
	v_writelane_b32 v252, s16, 30
	s_ashr_i32 s14, s25, 3
	s_lshr_b32 s6, s25, 3
	s_add_i32 s28, s24, s23
	v_writelane_b32 v252, s14, 31
	s_add_i32 s14, s52, 0x327f
	s_min_i32 s24, s34, 0x327f
	s_cmpk_lt_i32 s34, 0x480
	v_writelane_b32 v252, s24, 32
	s_cselect_b32 s24, 0, 0xfffffb80
	s_cselect_b32 s84, 0, 0x480000
	s_cmpk_gt_i32 s34, 0x8ff
	v_writelane_b32 v252, s24, 33
	s_cselect_b64 s[24:25], -1, 0
	v_writelane_b32 v252, s24, 34
	s_cmpk_gt_i32 s34, 0x97f
	v_rcp_iflag_f32_e32 v2, v1
	v_writelane_b32 v252, s25, 35
	s_cselect_b64 s[24:25], -1, 0
	v_writelane_b32 v252, s24, 36
	s_cmpk_gt_i32 s34, 0x9ff
	v_mov_b32_e32 v211, 6
	v_writelane_b32 v252, s25, 37
	s_cselect_b64 s[24:25], -1, 0
	v_writelane_b32 v252, s24, 38
	s_cmpk_gt_i32 s34, 0xc3f
	v_mov_b32_e32 v212, 0x41b17218
	v_writelane_b32 v252, s25, 39
	s_cselect_b64 s[24:25], -1, 0
	v_writelane_b32 v252, s24, 40
	s_cmpk_gt_i32 s34, 0xd3f
	v_mov_b32_e32 v213, 0x3e38aa3b
	v_writelane_b32 v252, s25, 41
	s_cselect_b64 s[24:25], -1, 0
	v_writelane_b32 v252, s24, 42
	s_cmpk_gt_i32 s34, 0x117f
	s_movk_i32 s50, 0x1200
	v_writelane_b32 v252, s25, 43
	s_cselect_b64 s[24:25], -1, 0
	v_writelane_b32 v252, s24, 44
	s_cmpk_gt_i32 s34, 0x127f
	s_mov_b32 s51, 0x800000
	v_writelane_b32 v252, s25, 45
	s_cselect_b64 s[24:25], -1, 0
	v_writelane_b32 v252, s24, 46
	s_cmpk_gt_i32 s34, 0x167f
	s_mov_b32 s48, 0x5040100
	v_writelane_b32 v252, s25, 47
	s_cselect_b64 s[24:25], -1, 0
	v_writelane_b32 v252, s24, 48
; #define PG8_LAS __attribute__((address_space(3)))
; DI unsigned xb_add(unsigned* p, unsigned v) { return __hip_atomic_fetch_add(p, v, __ATOMIC_RELAXED, __HIP_MEMORY_SCOPE_AGENT); }
; DI unsigned xb_xcc_id() { return (unsigned)__builtin_amdgcn_s_getreg((3 << 11) | 20) & 0xFu; }
;     __host__ __device__ bool next(int i, Unit& u) const {
;         const long L = (long)i * G + c; if (L >= nwg) return false;
;         int wgid = (int)L; { const int q = nwg / NXCD, r = nwg % NXCD, xcd = wgid % NXCD, off = wgid / NXCD; wgid = (xcd < r ? xcd * (q + 1) : r * (q + 1) + (xcd - r) * q) + off; }
;         const int nig = WGM * nN, gid = wgid / nig, fm = gid * WGM, gsz = (nM - fm) < WGM ? (nM - fm) : WGM;
;         u.pm = fm + ((wgid % nig) % gsz); u.pn = (wgid % nig) / gsz; return true;
; __global__ void __launch_bounds__(512, 2) mega(Params pp) {
;   extern __shared__ __attribute__((aligned(16))) char smem0[];
;   cg::grid_group grid = cg::this_grid();
;   const int wv8_ = __builtin_amdgcn_readfirstlane((int)threadIdx.x >> 6);
;   const int hb_ = wv8_ >> 2, wv_ = wv8_ & 3;
;   const int vb_ = (int)blockIdx.x * 2 + hb_, nvb_ = (int)gridDim.x * 2;
;   {
;     volatile PG8_LAS unsigned* st = (volatile PG8_LAS unsigned*)(smem0 + 2 * HALF_LDS);
;     const bool lead0 = tidx(wv8_) == 0;
;     if (lead0) { st[0] = 0u; st[1] = 0u; (void)xb_add(&((unsigned*)(pp.c.ws + WS_BAR))[XB_XCNT(xb_xcc_id())], 1u); }
;     __syncthreads();
;   }
;   if (pp.ph1 < 0) grid.sync();
; #pragma unroll 1
;   for (int ph = pp.ph0; ph < pp.ph1; ++ph) {
;     const Ctx& p = pp.c;
;     size_t wsoff_ = 0; asm volatile("" : "+s"(wsoff_));
;     char* ws_ = pp.c.ws + wsoff_;
;     unsigned smoff_ = 0; asm volatile("" : "+v"(smoff_));
;     char* smem = smem0 + hb_ * HALF_LDS + smoff_;
;     const u16* WT = (const u16*)(ws_ + WS_WT);
;     u16* H = (u16*)(ws_ + WS_H);
;     u16* Pm = (u16*)(ws_ + WS_P);
;     const int code = pp.ops[ph];
;     const int op = code & 15, l = (code >> 4) & 3, half = (code >> 6) & 1;
;     const int kind = l % 3, j = l / 3;
;     const float* xcur = (code >> 7) ? p.x : p.out;
;     switch (op) {
	s_cmpk_gt_i32 s34, 0x1a7f
	s_mov_b32 s49, 0x7f800000
	v_writelane_b32 v252, s25, 49
	s_cselect_b64 s[24:25], -1, 0
	v_writelane_b32 v252, s24, 50
	s_cmpk_gt_i32 s34, 0x1e7f
	s_mov_b32 s43, 0x3f317217
	v_writelane_b32 v252, s25, 51
	s_cselect_b64 s[24:25], -1, 0
	v_writelane_b32 v252, s24, 52
	s_cmpk_gt_i32 s34, 0x227f
	s_mov_b32 s46, 0x409b43d5
	v_writelane_b32 v252, s25, 53
	s_cselect_b64 s[24:25], -1, 0
	v_writelane_b32 v252, s24, 54
	s_cmpk_gt_i32 s34, 0x267f
	s_mov_b32 s47, 0x200000
	v_writelane_b32 v252, s25, 55
	s_cselect_b64 s[24:25], -1, 0
	v_writelane_b32 v252, s24, 56
	s_cmpk_gt_i32 s34, 0x2a7f
	s_mov_b64 s[70:71], 0
	v_writelane_b32 v252, s25, 57
	s_cselect_b64 s[24:25], -1, 0
	v_writelane_b32 v252, s24, 58
	s_cmpk_gt_i32 s34, 0x2e7f
	s_mov_b64 s[92:93], 0x80
	v_writelane_b32 v252, s25, 59
	s_cselect_b64 s[24:25], -1, 0
	v_writelane_b32 v252, s24, 60
	s_add_i32 s21, s21, s20
	s_add_i32 s20, s22, s20
	v_writelane_b32 v252, s25, 61
	s_ashr_i32 s24, s21, 31
	s_lshr_b32 s24, s24, 25
	s_add_i32 s24, s21, s24
	s_and_b32 s25, s24, 0xff80
	s_sub_i32 s21, s21, s25
	s_bfe_i32 s25, s21, 0x80000
	s_bfe_u32 s25, s25, 0x3000c
	s_add_i32 s25, s21, s25
	s_and_b32 s26, s25, 0xf8
	s_sub_i32 s26, s21, s26
	s_ashr_i32 s21, s20, 31
	s_lshr_b32 s21, s21, 27
	s_add_i32 s21, s20, s21
	s_and_b32 s22, s21, 0xffe0
	s_sub_i32 s20, s20, s22
	s_bfe_i32 s22, s20, 0x80000
	s_bfe_u32 s22, s22, 0x3000c
	s_add_i32 s22, s20, s22
	s_and_b32 s27, s22, 0xf8
	s_sub_i32 s20, s20, s27
	s_ashr_i32 s21, s21, 5
	s_lshl_b32 s21, s21, 3
	s_sext_i32_i8 s20, s20
	s_add_i32 s31, s21, s20
	s_ashr_i32 s20, s28, 3
	s_ashr_i32 s21, s20, 31
	v_writelane_b32 v252, s28, 62
	s_lshl_b64 s[28:29], s[20:21], 12
	s_lshl_b32 s20, s23, 8
	s_abs_i32 s23, s52
	v_cvt_f32_u32_e32 v0, s23
	s_and_b32 s20, s20, 0x700
	s_or_b32 s28, s28, s20
	s_sub_i32 s20, 0, s23
	v_rcp_iflag_f32_e32 v0, v0
	v_writelane_b32 v253, s28, 0
	s_and_b32 s13, s13, 0xff800000
	v_writelane_b32 v252, s17, 63
	v_mul_f32_e32 v0, 0x4f7ffffe, v0
	v_cvt_u32_f32_e32 v0, v0
	v_writelane_b32 v253, s29, 1
	s_mov_b64 s[80:81], 0x1000
	v_readfirstlane_b32 s21, v0
	s_mul_i32 s20, s20, s21
	s_mul_hi_u32 s20, s21, s20
	s_add_i32 s27, s21, s20
	s_abs_i32 s20, s19
	s_mul_hi_u32 s28, s20, s27
	s_mul_i32 s21, s28, s23
	s_sub_i32 s29, s20, s21
	s_ashr_i32 s20, s24, 7
	s_bfe_i32 s21, s25, 0x80000
	s_lshl_b32 s20, s20, 3
	s_sext_i32_i16 s21, s21
	s_sext_i32_i8 s24, s26
	s_add_i32 s24, s20, s24
	s_ashr_i32 s20, s21, 3
	v_writelane_b32 v253, s20, 2
	s_lshr_b32 s20, s21, 3
	s_bfe_i64 s[20:21], s[20:21], 0x100000
	s_lshl_b64 s[20:21], s[20:21], 19
	v_writelane_b32 v253, s20, 3
	s_ashr_i32 s25, s24, 31
	v_cvt_f32_i32_e32 v0, s11
	v_writelane_b32 v253, s21, 4
	s_lshl_b32 s20, s30, 19
	v_writelane_b32 v253, s30, 5
	s_and_b32 s20, s20, 0x380000
	v_writelane_b32 v253, s20, 6
	v_writelane_b32 v253, s13, 7
	s_lshl_b32 s13, s18, 19
	v_writelane_b32 v253, s13, 8
	s_bfe_i32 s13, s22, 0x80000
	s_sext_i32_i16 s13, s13
	s_ashr_i32 s18, s13, 3
	v_writelane_b32 v253, s18, 9
	s_lshr_b32 s18, s13, 3
	s_bfe_i64 s[20:21], s[18:19], 0x100000
	v_writelane_b32 v253, s20, 10
	s_load_dword s13, s[62:63], 0xf8
	v_mul_f32_e32 v2, v0, v2
	v_writelane_b32 v253, s21, 11
	s_bfe_i64 s[20:21], s[6:7], 0x100000
	s_lshl_b64 s[20:21], s[20:21], 19
	v_writelane_b32 v253, s20, 12
	s_waitcnt lgkmcnt(0)
	s_bfe_i32 s18, s13, 0x1001e
	s_ashr_i32 s13, s31, 31
	v_writelane_b32 v253, s21, 13
	v_writelane_b32 v253, s31, 14
	v_writelane_b32 v253, s13, 15
	s_mov_b32 s20, s24
	s_ashr_i32 s6, s19, 31
	v_writelane_b32 v253, s20, 16
	s_xor_b32 s6, s6, s18
	s_add_i32 s13, s28, 1
	s_sub_i32 s19, s29, s23
	v_writelane_b32 v253, s21, 17
	s_lshl_b64 s[20:21], s[24:25], 19
	s_cmp_ge_u32 s29, s23
	v_writelane_b32 v253, s20, 18
	s_cselect_b32 s13, s13, s28
	s_cselect_b32 s19, s19, s29
	v_writelane_b32 v253, s21, 19
	s_add_i32 s20, s13, 1
	s_cmp_ge_u32 s19, s23
	s_cselect_b32 s13, s20, s13
	s_xor_b32 s13, s13, s6
	s_sub_i32 s6, s13, s6
	s_cmp_gt_i32 s6, 0
	v_writelane_b32 v253, s6, 20
	s_cselect_b64 s[20:21], -1, 0
	s_abs_i32 s6, s15
	s_mul_hi_u32 s13, s6, s27
	s_mul_i32 s19, s13, s23
	v_writelane_b32 v253, s20, 21
	s_sub_i32 s6, s6, s19
	s_ashr_i32 s15, s15, 31
	v_writelane_b32 v253, s21, 22
	s_xor_b32 s15, s15, s18
	s_add_i32 s19, s13, 1
	s_sub_i32 s20, s6, s23
	s_cmp_ge_u32 s6, s23
	s_cselect_b32 s13, s19, s13
	s_cselect_b32 s6, s20, s6
	s_add_i32 s19, s13, 1
	s_cmp_ge_u32 s6, s23
	s_cselect_b32 s6, s19, s13
	s_xor_b32 s6, s6, s15
	s_sub_i32 s6, s6, s15
	s_cmp_gt_i32 s6, 0
	v_writelane_b32 v253, s6, 23
	s_cselect_b64 s[20:21], -1, 0
	s_abs_i32 s6, s12
	s_mul_hi_u32 s13, s6, s27
	s_mul_i32 s15, s13, s23
	s_sub_i32 s6, s6, s15
	s_ashr_i32 s12, s12, 31
	s_xor_b32 s12, s12, s18
	s_add_i32 s15, s13, 1
	s_sub_i32 s19, s6, s23
	s_cmp_ge_u32 s6, s23
	s_cselect_b32 s13, s15, s13
	s_cselect_b32 s6, s19, s6
	s_add_i32 s15, s13, 1
	s_cmp_ge_u32 s6, s23
	s_cselect_b32 s6, s15, s13
	s_xor_b32 s6, s6, s12
	v_writelane_b32 v253, s20, 24
	s_sub_i32 s6, s6, s12
	s_cmp_gt_i32 s6, 0
	v_writelane_b32 v253, s21, 25
	v_writelane_b32 v253, s6, 26
	s_cselect_b64 s[12:13], -1, 0
	v_trunc_f32_e32 v2, v2
	v_writelane_b32 v253, s12, 27
	v_fma_f32 v0, -v2, v1, v0
	s_ashr_i32 s6, s11, 30
	v_writelane_b32 v253, s13, 28
	v_cmp_ge_f32_e64 s[12:13], |v0|, v1
	v_cvt_i32_f32_e32 v0, v2
	s_or_b32 s6, s6, 1
	s_and_b64 s[12:13], s[12:13], exec
	v_cvt_f32_ubyte0_e32 v1, s7
	v_readfirstlane_b32 s12, v0
	v_cvt_f32_i32_e32 v0, s8
	v_rcp_iflag_f32_e32 v2, v1
	s_cselect_b32 s6, s6, 0
	s_add_i32 s6, s12, s6
	s_mul_i32 s10, s6, s10
	v_mul_f32_e32 v2, v0, v2
	s_sub_i32 s10, s11, s10
	v_trunc_f32_e32 v2, v2
	s_sext_i32_i8 s10, s10
	v_fma_f32 v0, -v2, v1, v0
	s_add_i32 s9, s9, s10
	v_cmp_ge_f32_e64 s[10:11], |v0|, v1
	v_cvt_i32_f32_e32 v0, v2
	v_writelane_b32 v253, s9, 29
	s_ashr_i32 s9, s8, 30
	s_or_b32 s9, s9, 1
	s_and_b64 s[10:11], s[10:11], exec
	s_cselect_b32 s9, s9, 0
	v_readfirstlane_b32 s10, v0
	s_add_i32 s9, s10, s9
	s_mul_i32 s7, s9, s7
	s_sub_i32 s7, s8, s7
	s_sext_i32_i16 s7, s7
	s_add_i32 s1, s1, s7
	s_abs_i32 s7, s14
	s_mul_hi_u32 s8, s7, s27
	s_mul_i32 s10, s8, s23
	v_writelane_b32 v253, s1, 30
	s_ashr_i32 s1, s14, 31
	s_sub_i32 s7, s7, s10
	s_xor_b32 s1, s1, s18
	s_add_i32 s10, s8, 1
	s_sub_i32 s11, s7, s23
	s_cmp_ge_u32 s7, s23
	s_cselect_b32 s8, s10, s8
	s_cselect_b32 s7, s11, s7
	s_add_i32 s10, s8, 1
	s_cmp_ge_u32 s7, s23
	s_cselect_b32 s7, s10, s8
	s_load_dword s29, s[62:63], 0xf8
	s_load_dwordx4 s[24:27], s[62:63], 0xa0
	s_xor_b32 s7, s7, s1
	s_sub_i32 s1, s7, s1
	s_cmp_gt_i32 s1, 0
	v_writelane_b32 v253, s1, 31
	s_cselect_b64 s[10:11], -1, 0
	v_writelane_b32 v253, s10, 32
	v_readlane_b32 s28, v252, 30
	v_mov_b32_e32 v1, 0
	v_writelane_b32 v253, s11, 33
	s_waitcnt lgkmcnt(0)
; #define PG8_LAS __attribute__((address_space(3)))
; __global__ void __launch_bounds__(512, 2) mega(Params pp) {
;     ...
;   for (int ph = pp.ph0; ph < pp.ph1; ++ph) {
;     const Ctx& p = pp.c;
;     size_t wsoff_ = 0; asm volatile("" : "+s"(wsoff_));
;     char* ws_ = pp.c.ws + wsoff_;
;     unsigned smoff_ = 0; asm volatile("" : "+v"(smoff_));
;     char* smem = smem0 + hb_ * HALF_LDS + smoff_;
;     const u16* WT = (const u16*)(ws_ + WS_WT);
;     u16* H = (u16*)(ws_ + WS_H);
;     u16* Pm = (u16*)(ws_ + WS_P);
;     const int code = pp.ops[ph];
;     const int op = code & 15, l = (code >> 4) & 3, half = (code >> 6) & 1;
;     const int kind = l % 3, j = l / 3;
;     const float* xcur = (code >> 7) ? p.x : p.out;
;     switch (op) {
;       case OP_CONVERT: phase_convert(wv_, vb_, nvb_, ws_, p, smem); break;
;       case OP_NORM_MIX: phase_norm(wv_, vb_, nvb_, xcur, p.norm_mix + l * DM, H); break;
;       case OP_GEMM_IN:
;         if (kind == 0) { pg8::EpiB16HN E; E.O = Pm; E.ldc = 4608; E.ncols_norm = 3072; E.nq_cols = 1536; E.gq = p.a_q_gain + j * 64; E.gk = p.a_k_gain + j * 64; E.T = (PG8_LAS float*)(smem0 + 131072);
	s_add_u32 s10, s26, 0x6603e00
	s_addc_u32 s11, s27, 0
	v_writelane_b32 v253, s10, 34
	s_lshl_b64 s[12:13], s[52:53], 12
	s_lshl_b32 s1, s2, 8
	v_writelane_b32 v253, s11, 35
	v_writelane_b32 v253, s12, 36
	s_ashr_i32 s45, s44, 31
	s_and_b32 s1, s1, 0x700
	v_writelane_b32 v253, s13, 37
	s_lshl_b64 s[12:13], s[34:35], 11
	v_writelane_b32 v253, s12, 38
	s_or_b32 s1, s4, s1
	s_lshl_b64 s[18:19], s[44:45], 11
	v_writelane_b32 v253, s13, 39
	s_lshl_b64 s[12:13], s[52:53], 13
	v_writelane_b32 v253, s12, 40
	s_lshl_b64 s[54:55], s[44:45], 12
	s_lshl_b64 s[10:11], s[52:53], 9
	v_writelane_b32 v253, s13, 41
	s_lshl_b64 s[12:13], s[52:53], 11
	v_writelane_b32 v253, s12, 42
	s_add_u32 s4, s26, s1
	s_addc_u32 s5, s27, s5
	v_writelane_b32 v253, s13, 43
	v_writelane_b32 v253, s4, 44
	s_mov_b32 s30, s36
	s_mov_b32 s31, s42
	v_writelane_b32 v253, s5, 45
	s_lshl_b64 s[4:5], s[2:3], 19
	s_add_u32 s1, s26, s4
	s_addc_u32 s4, s27, s5
	s_add_u32 s12, s1, 0x12600040
	s_addc_u32 s13, s4, 0
	s_lshl_b64 s[2:3], s[2:3], 7
	s_add_u32 s1, s26, s2
	s_addc_u32 s2, s27, s3
	v_writelane_b32 v253, s12, 46
	s_add_u32 s4, s1, 0x1ef80000
	s_addc_u32 s5, s2, 0
	v_writelane_b32 v253, s13, 47
	v_writelane_b32 v253, s4, 48
	s_lshl_b32 s0, s0, 12
	s_lshl_b32 s1, s28, 13
	v_writelane_b32 v253, s5, 49
	s_add_i32 s0, s1, s0
	v_writelane_b32 v253, s0, 50
	s_sext_i32_i8 s0, s6
	v_writelane_b32 v253, s0, 51
	s_sext_i32_i16 s0, s9
	v_writelane_b32 v253, s0, 52
	s_add_i32 s2, s37, 0x4700
	v_writelane_b32 v253, s2, 53
	s_add_i32 s2, s37, 0x10000
	v_writelane_b32 v253, s2, 54
	s_add_i32 s2, s37, 0x10400
	v_writelane_b32 v253, s2, 55
	s_lshl_b32 s2, s29, 13
	v_writelane_b32 v253, s2, 56
	s_add_i32 s2, s37, 0x11000
	v_writelane_b32 v253, s2, 57
	s_add_u32 s2, s26, 0x13c00000
	v_writelane_b32 v253, s2, 58
	s_addc_u32 s2, s27, 0
	v_writelane_b32 v253, s2, 59
	s_add_u32 s2, s26, 0x15000000
	v_writelane_b32 v253, s2, 60
	s_addc_u32 s2, s27, 0
	v_writelane_b32 v253, s2, 61
	s_lshl_b64 s[2:3], s[34:35], 12
	v_writelane_b32 v253, s2, 62
	s_lshl_b64 s[20:21], s[52:53], 14
	s_mul_i32 s0, s29, 0x600
	v_writelane_b32 v253, s3, 63
	s_add_u32 s2, s10, s38
	v_writelane_b32 v254, s10, 0
	s_addc_u32 s3, s11, s39
	s_mul_hi_i32 s1, s52, 0x300
	v_writelane_b32 v254, s11, 1
	v_writelane_b32 v254, s2, 2
	v_mov_b32_e32 v242, v1
	v_mov_b32_e32 v243, v1
	v_writelane_b32 v254, s3, 3
	s_add_u32 s2, s0, s38
	v_writelane_b32 v254, s0, 4
	s_addc_u32 s3, s1, s39
	v_mov_b32_e32 v244, v1
	v_writelane_b32 v254, s1, 5
	v_writelane_b32 v254, s2, 6
	s_add_u32 s0, s40, s38
	v_mov_b32_e32 v245, v1
	v_writelane_b32 v254, s3, 7
	v_writelane_b32 v254, s38, 8
	s_addc_u32 s1, s41, s39
	s_movk_i32 s36, 0x1800
	v_writelane_b32 v254, s39, 9
	v_writelane_b32 v254, s0, 10
	s_mov_b32 s39, 0xff800000
	s_mov_b32 s38, 0x100000
	v_writelane_b32 v254, s1, 11
	v_writelane_b32 v254, s37, 12
	s_add_i32 s0, s37, 0x8394
	v_writelane_b32 v254, s0, 13
	s_mov_b32 s0, s34
	v_writelane_b32 v254, s0, 14
	s_movk_i32 s37, 0x80
	s_movk_i32 s42, 0xc00
	v_writelane_b32 v254, s1, 15
	s_add_i32 s0, s34, s52
	v_writelane_b32 v254, s0, 16
	s_add_i32 s0, 0, 0x20000
	v_writelane_b32 v254, s0, 17
	s_add_i32 s0, 0, 0x25800
	v_writelane_b32 v254, s0, 18
	s_add_i32 s0, 0, 0x25804
	v_writelane_b32 v254, s0, 19
	s_load_dwordx8 s[0:7], s[62:63], 0x40
	v_writelane_b32 v254, s84, 20
	s_nop 1
	v_writelane_b32 v254, s85, 21
	s_waitcnt lgkmcnt(0)
	v_writelane_b32 v254, s0, 22
	s_nop 1
	v_writelane_b32 v254, s1, 23
	v_writelane_b32 v254, s2, 24
	v_writelane_b32 v254, s3, 25
	v_writelane_b32 v254, s4, 26
	v_writelane_b32 v254, s5, 27
	v_writelane_b32 v254, s6, 28
	v_writelane_b32 v254, s7, 29
	s_load_dwordx16 s[0:15], s[62:63], 0x0
	s_waitcnt lgkmcnt(0)
	v_writelane_b32 v254, s0, 30
	s_nop 1
	v_writelane_b32 v254, s1, 31
	v_writelane_b32 v254, s2, 32
	v_writelane_b32 v254, s3, 33
	v_writelane_b32 v254, s4, 34
	v_writelane_b32 v254, s5, 35
	v_writelane_b32 v254, s6, 36
	v_writelane_b32 v254, s7, 37
	v_writelane_b32 v254, s8, 38
	v_writelane_b32 v254, s9, 39
	v_writelane_b32 v254, s10, 40
	v_writelane_b32 v254, s11, 41
	v_writelane_b32 v254, s12, 42
	v_writelane_b32 v254, s13, 43
	v_writelane_b32 v254, s14, 44
	v_writelane_b32 v254, s15, 45
	v_writelane_b32 v254, s62, 46
	s_nop 1
	v_writelane_b32 v254, s63, 47
	v_writelane_b32 v254, s44, 48
	s_nop 1
	v_writelane_b32 v254, s45, 49
	v_writelane_b32 v254, s68, 50
	s_nop 1
	v_writelane_b32 v254, s69, 51
	v_writelane_b32 v254, s18, 52
	s_nop 1
	v_writelane_b32 v254, s19, 53
	v_writelane_b32 v254, s54, 54
	s_nop 1
	v_writelane_b32 v254, s55, 55
	v_writelane_b32 v254, s52, 56
	s_nop 1
	v_writelane_b32 v254, s53, 57
	v_writelane_b32 v254, s20, 58
	s_nop 1
	v_writelane_b32 v254, s21, 59
	s_branch .LBB0_20

; DI int t5_bucket(int dist) {
;   if (dist < 16) return dist;
;   float lp = logf((float)dist / 16.0f) / 4.852030263919617f * 16.0f;
;   int b = 16 + (int)lp;
;   return b < 31 ? b : 31;
; }
; DI void phase_attn_a(int wv_, int vb_, int nvb_, char* ws_, const Ctx& p, char* smem) {
;     ...
;   const int tid = tidx(wv_), lane = tid & 63, wave = tid >> 6, c = lane & 31, h = lane >> 5;
;   for (int k_ = 0; k_ < (6144 + nvb_ - 1) / nvb_; ++k_) {
;     const int u = (vb_ + k_ * nvb_ < 6144) ? vb_ + k_ * nvb_ : 6143;
;     const int head = u & 7, g = (u >> 3) % 3, rest = u / 24, idx = rest & 31, b = rest >> 5;
;     const int dil = (g == 0) ? 1 : ((g == 1) ? 4 : 16);
;     const int nbper = 32 / dil, r = idx / nbper, nb = idx % nbper;
;     u16* Og = (g == 0) ? (u16*)(ws_ + WS_H) : ((g == 1) ? (u16*)(ws_ + WS_H + 32 * MiB) : (u16*)(ws_ + WS_E));
;     float* lse = (float*)(ws_ + WS_LSE) + (size_t)g * NTOK * 8;
;     if (tid <= 128) sBias[tid] = p.rel_bias[t5_bucket(tid * dil) * 40 + g * 8 + head] * 1.4426950408889634f;
.LBB0_493:
	v_writelane_b32 v255, s54, 5
	s_cmp_lt_i32 s23, 2
	s_mov_b64 s[2:3], -1
	v_writelane_b32 v255, s55, 6
	s_cbranch_scc1 .LBB0_764
	s_cmp_gt_i32 s23, 2
	s_cbranch_scc0 .LBB0_552
	v_readlane_b32 s2, v253, 27
	v_readlane_b32 s3, v253, 28
	s_mov_b32 s0, s33
	v_mov_b32_e32 v0, v204
	s_andn2_b64 vcc, exec, s[2:3]
	s_cbranch_vccnz .LBB0_551
	s_mov_b32 s60, s33
	v_readlane_b32 s35, v253, 26
	v_readlane_b32 s44, v254, 14
	v_readlane_b32 s45, v254, 56
	v_readlane_b32 s56, v254, 32
	v_readlane_b32 s57, v254, 33
	v_and_b32_e32 v196, 31, v204
	v_lshrrev_b32_e32 v197, 5, v204
	v_lshl_add_u32 v202, s60, 6, v204
	s_lshl_b32 s0, s60, 5
	v_add_u32_e32 v200, s0, v196
	v_lshlrev_b32_e32 v201, 4, v197
	v_lshlrev_b32_e32 v239, 3, v197
	v_add_u32_e32 v241, 0xffffff80, v202
	v_lshl_add_u32 v203, v202, 1, v214
	v_mul_u32_u24_e32 v198, 0x208, v196
	v_add_u32_e32 v198, v198, v214
	s_lshl_b32 s1, s60, 6
	v_add_u32_e32 v198, s1, v198
	v_add_u32_e32 v209, v198, v239
	v_lshl_add_u32 v198, v196, 2, v214
	v_sub_u32_e32 v198, v198, v201
	v_add_u32_e32 v216, 0x10400, v198
	v_lshl_add_u32 v198, v202, 2, v214
	v_add_u32_e32 v217, 0x10400, v198
	v_add_u32_e32 v198, 0xffffffe1, v202
	v_cmp_gt_u32_e32 vcc, 0x81, v198
	s_mov_b64 s[66:67], vcc
	v_max_i32_e32 v198, 0, v198
	v_min_u32_e32 v198, 0x80, v198
	v_lshlrev_b32_e32 v199, 0, v198
	v_mov_b32_e32 v246, 16
	v_cmp_le_u32_e32 vcc, 22, v199
	s_nop 1
	v_addc_co_u32_e32 v246, vcc, 0, v246, vcc
	v_cmp_le_u32_e32 vcc, 30, v199
	s_nop 1
	v_addc_co_u32_e32 v246, vcc, 0, v246, vcc
	v_cmp_le_u32_e32 vcc, 40, v199
	s_nop 1
	v_addc_co_u32_e32 v246, vcc, 0, v246, vcc
	v_cmp_le_u32_e32 vcc, 54, v199
	s_nop 1
	v_addc_co_u32_e32 v246, vcc, 0, v246, vcc
	v_cmp_le_u32_e32 vcc, 0x49, v199
	s_nop 1
	v_addc_co_u32_e32 v246, vcc, 0, v246, vcc
	v_cmp_le_u32_e32 vcc, 0x63, v199
	s_nop 1
	v_addc_co_u32_e32 v246, vcc, 0, v246, vcc
	v_cmp_le_u32_e32 vcc, 0x86, v199
	s_nop 1
	v_addc_co_u32_e32 v246, vcc, 0, v246, vcc
	v_cmp_le_u32_e32 vcc, 0xb6, v199
	s_nop 1
	v_addc_co_u32_e32 v246, vcc, 0, v246, vcc
	v_cmp_le_u32_e32 vcc, 0xf6, v199
	s_nop 1
	v_addc_co_u32_e32 v246, vcc, 0, v246, vcc
	v_cmp_le_u32_e32 vcc, 0x14c, v199
	s_nop 1
	v_addc_co_u32_e32 v246, vcc, 0, v246, vcc
	v_cmp_le_u32_e32 vcc, 0x1c2, v199
	s_nop 1
	v_addc_co_u32_e32 v246, vcc, 0, v246, vcc
	v_cmp_le_u32_e32 vcc, 0x261, v199
	s_nop 1
	v_addc_co_u32_e32 v246, vcc, 0, v246, vcc
	v_cmp_le_u32_e32 vcc, 0x339, v199
	s_nop 1
	v_addc_co_u32_e32 v246, vcc, 0, v246, vcc
	v_cmp_le_u32_e32 vcc, 0x45d, v199
	s_nop 1
	v_addc_co_u32_e32 v246, vcc, 0, v246, vcc
	v_cmp_le_u32_e32 vcc, 0x5e9, v199
	s_nop 1
	v_addc_co_u32_e32 v246, vcc, 0, v246, vcc
	v_cmp_gt_u32_e32 vcc, 16, v199
	s_nop 1
	v_cndmask_b32_e32 v246, v246, v199, vcc
	v_mul_u32_u24_e32 v218, 0xa0, v246
	v_lshlrev_b32_e32 v199, 2, v198
	v_mov_b32_e32 v246, 16
	v_cmp_le_u32_e32 vcc, 22, v199
	s_nop 1
	v_addc_co_u32_e32 v246, vcc, 0, v246, vcc
	v_cmp_le_u32_e32 vcc, 30, v199
	s_nop 1
	v_addc_co_u32_e32 v246, vcc, 0, v246, vcc
	v_cmp_le_u32_e32 vcc, 40, v199
	s_nop 1
	v_addc_co_u32_e32 v246, vcc, 0, v246, vcc
	v_cmp_le_u32_e32 vcc, 54, v199
	s_nop 1
	v_addc_co_u32_e32 v246, vcc, 0, v246, vcc
	v_cmp_le_u32_e32 vcc, 0x49, v199
	s_nop 1
	v_addc_co_u32_e32 v246, vcc, 0, v246, vcc
	v_cmp_le_u32_e32 vcc, 0x63, v199
	s_nop 1
	v_addc_co_u32_e32 v246, vcc, 0, v246, vcc
	v_cmp_le_u32_e32 vcc, 0x86, v199
	s_nop 1
	v_addc_co_u32_e32 v246, vcc, 0, v246, vcc
	v_cmp_le_u32_e32 vcc, 0xb6, v199
	s_nop 1
	v_addc_co_u32_e32 v246, vcc, 0, v246, vcc
	v_cmp_le_u32_e32 vcc, 0xf6, v199
	s_nop 1
	v_addc_co_u32_e32 v246, vcc, 0, v246, vcc
	v_cmp_le_u32_e32 vcc, 0x14c, v199
	s_nop 1
	v_addc_co_u32_e32 v246, vcc, 0, v246, vcc
	v_cmp_le_u32_e32 vcc, 0x1c2, v199
	s_nop 1
	v_addc_co_u32_e32 v246, vcc, 0, v246, vcc
	v_cmp_le_u32_e32 vcc, 0x261, v199
	s_nop 1
	v_addc_co_u32_e32 v246, vcc, 0, v246, vcc
	v_cmp_le_u32_e32 vcc, 0x339, v199
	s_nop 1
	v_addc_co_u32_e32 v246, vcc, 0, v246, vcc
	v_cmp_le_u32_e32 vcc, 0x45d, v199
	s_nop 1
	v_addc_co_u32_e32 v246, vcc, 0, v246, vcc
	v_cmp_le_u32_e32 vcc, 0x5e9, v199
	s_nop 1
	v_addc_co_u32_e32 v246, vcc, 0, v246, vcc
	v_cmp_gt_u32_e32 vcc, 16, v199
	s_nop 1
	v_cndmask_b32_e32 v246, v246, v199, vcc
	v_mul_u32_u24_e32 v219, 0xa0, v246
	v_lshlrev_b32_e32 v199, 4, v198
	v_mov_b32_e32 v246, 16
	v_cmp_le_u32_e32 vcc, 22, v199
	s_nop 1
	v_addc_co_u32_e32 v246, vcc, 0, v246, vcc
	v_cmp_le_u32_e32 vcc, 30, v199
	s_nop 1
	v_addc_co_u32_e32 v246, vcc, 0, v246, vcc
	v_cmp_le_u32_e32 vcc, 40, v199
	s_nop 1
	v_addc_co_u32_e32 v246, vcc, 0, v246, vcc
	v_cmp_le_u32_e32 vcc, 54, v199
	s_nop 1
	v_addc_co_u32_e32 v246, vcc, 0, v246, vcc
	v_cmp_le_u32_e32 vcc, 0x49, v199
	s_nop 1
	v_addc_co_u32_e32 v246, vcc, 0, v246, vcc
	v_cmp_le_u32_e32 vcc, 0x63, v199
	s_nop 1
	v_addc_co_u32_e32 v246, vcc, 0, v246, vcc
	v_cmp_le_u32_e32 vcc, 0x86, v199
	s_nop 1
	v_addc_co_u32_e32 v246, vcc, 0, v246, vcc
	v_cmp_le_u32_e32 vcc, 0xb6, v199
	s_nop 1
	v_addc_co_u32_e32 v246, vcc, 0, v246, vcc
	v_cmp_le_u32_e32 vcc, 0xf6, v199
	s_nop 1
	v_addc_co_u32_e32 v246, vcc, 0, v246, vcc
	v_cmp_le_u32_e32 vcc, 0x14c, v199
	s_nop 1
	v_addc_co_u32_e32 v246, vcc, 0, v246, vcc
	v_cmp_le_u32_e32 vcc, 0x1c2, v199
	s_nop 1
	v_addc_co_u32_e32 v246, vcc, 0, v246, vcc
	v_cmp_le_u32_e32 vcc, 0x261, v199
	s_nop 1
	v_addc_co_u32_e32 v246, vcc, 0, v246, vcc
	v_cmp_le_u32_e32 vcc, 0x339, v199
	s_nop 1
	v_addc_co_u32_e32 v246, vcc, 0, v246, vcc
	v_cmp_le_u32_e32 vcc, 0x45d, v199
	s_nop 1
	v_addc_co_u32_e32 v246, vcc, 0, v246, vcc
	v_cmp_le_u32_e32 vcc, 0x5e9, v199
	s_nop 1
	v_addc_co_u32_e32 v246, vcc, 0, v246, vcc
	v_cmp_gt_u32_e32 vcc, 16, v199
	s_nop 1
	v_cndmask_b32_e32 v246, v246, v199, vcc
	v_mul_u32_u24_e32 v220, 0xa0, v246
	s_mov_b32 s64, 0
	s_mov_b32 s65, 0
	s_mov_b32 s0, 0
	s_cmp_eq_u32 s45, 0x200
	s_cbranch_scc0 .Lattn_map_old1
	s_lshr_b32 s1, s44, 1
	s_and_b32 s3, s1, 7
	s_lshr_b32 s1, s1, 3
	s_lshl_b32 s63, s3, 3
	s_lshr_b32 s68, s1, 2
	s_add_i32 s63, s63, s68
	s_lshl_b32 s0, s0, 6
	s_add_i32 s63, s63, s0
	s_and_b32 s1, s1, 3
	s_lshl_b32 s1, s1, 1
	s_and_b32 s68, s44, 1
	s_or_b32 s1, s1, s68
	s_lshl_b32 s0, s63, 3
	s_or_b32 s0, s0, s1
	s_branch .Lattn_map_done1
; DI void phase_attn_a(int wv_, int vb_, int nvb_, char* ws_, const Ctx& p, char* smem) {
;     ...
;     const int u = (vb_ + k_ * nvb_ < 6144) ? vb_ + k_ * nvb_ : 6143;
;     const int head = u & 7, g = (u >> 3) % 3, rest = u / 24, idx = rest & 31, b = rest >> 5;
;     const int dil = (g == 0) ? 1 : ((g == 1) ? 4 : 16);
;     const int nbper = 32 / dil, r = idx / nbper, nb = idx % nbper;
;     u16* Og = (g == 0) ? (u16*)(ws_ + WS_H) : ((g == 1) ? (u16*)(ws_ + WS_H + 32 * MiB) : (u16*)(ws_ + WS_E));
;     float* lse = (float*)(ws_ + WS_LSE) + (size_t)g * NTOK * 8;
;     if (tid <= 128) sBias[tid] = p.rel_bias[t5_bucket(tid * dil) * 40 + g * 8 + head] * 1.4426950408889634f;
;     {
;       const int kk = tid; const int ksub = nb * 128 - 128 + kk;
;       bf16x8 v[8];
;       if (ksub >= 0) {
;         const u16* vp = P + ((size_t)b * SEQ + (size_t)ksub * dil + r) * 4608 + 3072 + g * 512 + head * 64;
; #pragma unroll
;         for (int i = 0; i < 8; ++i) v[i] = *(const bf16x8*)(vp + i * 8);
;       } else {
; #pragma unroll
;         for (int i = 0; i < 8; ++i) v[i] = zero8();
;       }
; #pragma unroll
;       for (int i = 0; i < 8; ++i)
; #pragma unroll
;         for (int jj = 0; jj < 8; ++jj) Vt[(i * 8 + jj) * 260 + kk] = (u16)v[i][jj];
;     }
;     __syncthreads();
;     {
;       const int qi = 32 * wave + c;
;       const int qtok = (nb * 128 + qi) * dil + r;
;       const u16* qp = P + ((size_t)b * SEQ + qtok) * 4608 + g * 512 + head * 64;
;       bf16x8 qf[4];
; #pragma unroll
;       for (int ks = 0; ks < 4; ++ks) qf[ks] = *(const bf16x8*)(qp + ks * 16 + h * 8);
;       float mx = -INFINITY, sum = 0.f;
;       f32x16 oacc[2]; oacc[0] = zero16(); oacc[1] = zero16();
; #pragma unroll 1
;       for (int kb = 0; kb < 5; ++kb) {
;         const int kk = 32 * wave + 32 * kb + c; const int ksub0 = nb * 128 - 128 + kk;
;         bf16x8 kf[4];
;         if (ksub0 >= 0) {
;           const u16* kp = P + ((size_t)b * SEQ + (size_t)ksub0 * dil + r) * 4608 + 1536 + g * 512 + head * 64;
; #pragma unroll
;           for (int ks = 0; ks < 4; ++ks) kf[ks] = *(const bf16x8*)(kp + ks * 16 + h * 8);
.Lattn_map_old1:
	s_mul_i32 s0, s0, s45
	s_add_i32 s0, s0, s44
.Lattn_map_done1:
	s_min_i32 s0, s0, 0x17ff
	s_and_b32 s1, s0, 7
	s_lshr_b32 s3, s0, 3
	s_mul_hi_u32 s63, s3, 0xaaaaaaab
	s_lshr_b32 s63, s63, 1
	s_mul_i32 s68, s63, 3
	s_sub_i32 s62, s3, s68
	s_and_b32 s69, s63, 31
	s_lshr_b32 s70, s63, 5
	s_lshl_b32 s10, s62, 1
	s_sub_i32 s71, 5, s10
	s_lshr_b32 s11, s69, s71
	s_lshr_b32 s68, 32, s10
	s_add_i32 s68, s68, -1
	s_and_b32 s68, s69, s68
	s_lshl_b32 s12, s68, 7
	s_sub_i32 s71, 4, s60
	s_lshl_b32 s71, 1, s71
	s_add_i32 s71, s71, -1
	s_cmp_eq_u32 s68, 0
	s_cselect_b32 s13, s71, 0
	s_lshl_b32 s71, s62, 3
	s_add_i32 s71, s71, s1
	s_lshl_b32 s100, s71, 22
	s_lshl_b32 s101, s70, 19
	s_add_i32 s100, s100, s101
	s_add_u32 s8, s86, s100
	s_addc_u32 s9, s87, 0
	s_add_u32 s72, s8, 0x6000000
	s_addc_u32 s73, s9, 0
	s_add_u32 s74, s8, 0xc000000
	s_addc_u32 s75, s9, 0
	s_mov_b32 s100, 0x8600000
	s_cmp_eq_u32 s62, 0
	s_cselect_b32 s100, 0x6600000, s100
	s_cmp_eq_u32 s62, 2
	s_cselect_b32 s100, 0x1c600000, s100
	s_lshl_b32 s101, s70, 22
	s_add_i32 s100, s100, s101
	s_lshl_b32 s101, s1, 7
	s_add_i32 s100, s100, s101
	s_add_u32 s14, s78, s100
	s_addc_u32 s15, s79, 0
	s_lshl_b32 s100, s62, 20
	s_lshl_b32 s101, s70, 17
	s_add_i32 s100, s100, s101
	s_lshl_b32 s101, s1, 2
	s_add_i32 s100, s100, s101
	s_add_i32 s100, s100, 0x1e600000
	s_add_u32 s18, s78, s100
	s_addc_u32 s19, s79, 0
	s_lshl_b32 s61, s71, 2
	v_add_u32_e32 v231, s12, v200
	v_lshlrev_b32_e32 v196, s10, v231
	v_add_u32_e32 v196, s11, v196
	v_lshl_add_u32 v226, v196, 10, v239
	v_lshlrev_b32_e32 v228, 5, v196
	v_lshl_add_u32 v232, v196, 7, v201
	v_add_u32_e32 v223, s64, v203
	v_add_u32_e32 v224, s65, v217
	v_add_u32_e32 v230, s12, v241
	v_max_i32_e32 v230, 0, v230
	v_lshlrev_b32_e32 v230, s10, v230
	v_add_u32_e32 v230, s11, v230
	v_lshlrev_b32_e32 v230, 7, v230
	global_load_dwordx4 v[98:101], v230, s[74:75]
	global_load_dwordx4 v[102:105], v230, s[74:75] offset:16
	global_load_dwordx4 v[106:109], v230, s[74:75] offset:32
	global_load_dwordx4 v[110:113], v230, s[74:75] offset:48
	global_load_dwordx4 v[114:117], v230, s[74:75] offset:64
	global_load_dwordx4 v[118:121], v230, s[74:75] offset:80
	global_load_dwordx4 v[122:125], v230, s[74:75] offset:96
	global_load_dwordx4 v[126:129], v230, s[74:75] offset:112
	s_cmp_eq_u32 s62, 0
	s_cselect_b64 vcc, -1, 0
	v_cndmask_b32_e32 v196, v219, v218, vcc
	s_cmp_eq_u32 s62, 2
	s_cselect_b64 vcc, -1, 0
	v_cndmask_b32_e32 v196, v196, v220, vcc
	v_add_u32_e32 v196, s61, v196
	global_load_dword v229, v196, s[56:57]
	v_add_u32_e32 v246, 0xffffff80, v231
	v_max_i32_e32 v246, 0, v246
	v_lshlrev_b32_e32 v246, s10, v246
	v_add_u32_e32 v246, s11, v246
	v_lshl_add_u32 v246, v246, 7, v201
	global_load_dwordx4 v[2:5], v246, s[72:73]
	global_load_dwordx4 v[6:9], v246, s[72:73] offset:32
	global_load_dwordx4 v[10:13], v246, s[72:73] offset:64
	global_load_dwordx4 v[14:17], v246, s[72:73] offset:96
	v_add_u32_e32 v246, 0xffffffa0, v231
	v_max_i32_e32 v246, 0, v246
	v_lshlrev_b32_e32 v246, s10, v246
	v_add_u32_e32 v246, s11, v246
	v_lshl_add_u32 v246, v246, 7, v201
	global_load_dwordx4 v[18:21], v246, s[72:73]
	global_load_dwordx4 v[22:25], v246, s[72:73] offset:32
	global_load_dwordx4 v[26:29], v246, s[72:73] offset:64
	global_load_dwordx4 v[30:33], v246, s[72:73] offset:96
	v_add_u32_e32 v246, 0xffffffc0, v231
	v_max_i32_e32 v246, 0, v246
	v_lshlrev_b32_e32 v246, s10, v246
	v_add_u32_e32 v246, s11, v246
	v_lshl_add_u32 v246, v246, 7, v201
	global_load_dwordx4 v[34:37], v246, s[72:73]
	global_load_dwordx4 v[38:41], v246, s[72:73] offset:32
	global_load_dwordx4 v[42:45], v246, s[72:73] offset:64
	global_load_dwordx4 v[46:49], v246, s[72:73] offset:96
	v_add_u32_e32 v246, 0xffffffe0, v231
	v_max_i32_e32 v246, 0, v246
	v_lshlrev_b32_e32 v246, s10, v246
	v_add_u32_e32 v246, s11, v246
	v_lshl_add_u32 v246, v246, 7, v201
	global_load_dwordx4 v[50:53], v246, s[72:73]
	global_load_dwordx4 v[54:57], v246, s[72:73] offset:32
	global_load_dwordx4 v[58:61], v246, s[72:73] offset:64
	global_load_dwordx4 v[62:65], v246, s[72:73] offset:96
	v_mov_b32_e32 v246, v231
	v_max_i32_e32 v246, 0, v246
	v_lshlrev_b32_e32 v246, s10, v246
	v_add_u32_e32 v246, s11, v246
	v_lshl_add_u32 v246, v246, 7, v201
	global_load_dwordx4 v[66:69], v246, s[72:73]
	global_load_dwordx4 v[70:73], v246, s[72:73] offset:32
	global_load_dwordx4 v[74:77], v246, s[72:73] offset:64
	global_load_dwordx4 v[78:81], v246, s[72:73] offset:96
	global_load_dwordx4 v[82:85], v232, s[8:9]
	global_load_dwordx4 v[86:89], v232, s[8:9] offset:32
	global_load_dwordx4 v[90:93], v232, s[8:9] offset:64
	global_load_dwordx4 v[94:97], v232, s[8:9] offset:96
	s_waitcnt vmcnt(24)
; DI void phase_attn_a(int wv_, int vb_, int nvb_, char* ws_, const Ctx& p, char* smem) {
;     ...
;   for (int k_ = 0; k_ < (6144 + nvb_ - 1) / nvb_; ++k_) {
;     const int u = (vb_ + k_ * nvb_ < 6144) ? vb_ + k_ * nvb_ : 6143;
;     const int head = u & 7, g = (u >> 3) % 3, rest = u / 24, idx = rest & 31, b = rest >> 5;
;     const int dil = (g == 0) ? 1 : ((g == 1) ? 4 : 16);
;     const int nbper = 32 / dil, r = idx / nbper, nb = idx % nbper;
;     u16* Og = (g == 0) ? (u16*)(ws_ + WS_H) : ((g == 1) ? (u16*)(ws_ + WS_H + 32 * MiB) : (u16*)(ws_ + WS_E));
;     float* lse = (float*)(ws_ + WS_LSE) + (size_t)g * NTOK * 8;
;     if (tid <= 128) sBias[tid] = p.rel_bias[t5_bucket(tid * dil) * 40 + g * 8 + head] * 1.4426950408889634f;
;     {
;       const int kk = tid; const int ksub = nb * 128 - 128 + kk;
;       bf16x8 v[8];
;       if (ksub >= 0) {
;         const u16* vp = P + ((size_t)b * SEQ + (size_t)ksub * dil + r) * 4608 + 3072 + g * 512 + head * 64;
; #pragma unroll
;         for (int i = 0; i < 8; ++i) v[i] = *(const bf16x8*)(vp + i * 8);
;       } else {
; #pragma unroll
;         for (int i = 0; i < 8; ++i) v[i] = zero8();
;       }
; #pragma unroll
;       for (int i = 0; i < 8; ++i)
; #pragma unroll
;         for (int jj = 0; jj < 8; ++jj) Vt[(i * 8 + jj) * 260 + kk] = (u16)v[i][jj];
;     }
;     __syncthreads();
	ds_write_b16 v223, v98
	ds_write_b16_d16_hi v223, v98 offset:520
	ds_write_b16 v223, v99 offset:1040
	ds_write_b16_d16_hi v223, v99 offset:1560
	ds_write_b16 v223, v100 offset:2080
	ds_write_b16_d16_hi v223, v100 offset:2600
	ds_write_b16 v223, v101 offset:3120
	ds_write_b16_d16_hi v223, v101 offset:3640
	ds_write_b16 v223, v102 offset:4160
	ds_write_b16_d16_hi v223, v102 offset:4680
	ds_write_b16 v223, v103 offset:5200
	ds_write_b16_d16_hi v223, v103 offset:5720
	ds_write_b16 v223, v104 offset:6240
	ds_write_b16_d16_hi v223, v104 offset:6760
	ds_write_b16 v223, v105 offset:7280
	ds_write_b16_d16_hi v223, v105 offset:7800
	ds_write_b16 v223, v106 offset:8320
	ds_write_b16_d16_hi v223, v106 offset:8840
	ds_write_b16 v223, v107 offset:9360
	ds_write_b16_d16_hi v223, v107 offset:9880
	ds_write_b16 v223, v108 offset:10400
	ds_write_b16_d16_hi v223, v108 offset:10920
	ds_write_b16 v223, v109 offset:11440
	ds_write_b16_d16_hi v223, v109 offset:11960
	ds_write_b16 v223, v110 offset:12480
	ds_write_b16_d16_hi v223, v110 offset:13000
	ds_write_b16 v223, v111 offset:13520
	ds_write_b16_d16_hi v223, v111 offset:14040
	ds_write_b16 v223, v112 offset:14560
	ds_write_b16_d16_hi v223, v112 offset:15080
	ds_write_b16 v223, v113 offset:15600
	ds_write_b16_d16_hi v223, v113 offset:16120
	ds_write_b16 v223, v114 offset:16640
	ds_write_b16_d16_hi v223, v114 offset:17160
	ds_write_b16 v223, v115 offset:17680
	ds_write_b16_d16_hi v223, v115 offset:18200
	ds_write_b16 v223, v116 offset:18720
	ds_write_b16_d16_hi v223, v116 offset:19240
	ds_write_b16 v223, v117 offset:19760
	ds_write_b16_d16_hi v223, v117 offset:20280
	ds_write_b16 v223, v118 offset:20800
	ds_write_b16_d16_hi v223, v118 offset:21320
	ds_write_b16 v223, v119 offset:21840
	ds_write_b16_d16_hi v223, v119 offset:22360
	ds_write_b16 v223, v120 offset:22880
	ds_write_b16_d16_hi v223, v120 offset:23400
	ds_write_b16 v223, v121 offset:23920
	ds_write_b16_d16_hi v223, v121 offset:24440
	ds_write_b16 v223, v122 offset:24960
	ds_write_b16_d16_hi v223, v122 offset:25480
	ds_write_b16 v223, v123 offset:26000
	ds_write_b16_d16_hi v223, v123 offset:26520
	ds_write_b16 v223, v124 offset:27040
	ds_write_b16_d16_hi v223, v124 offset:27560
	ds_write_b16 v223, v125 offset:28080
	ds_write_b16_d16_hi v223, v125 offset:28600
	ds_write_b16 v223, v126 offset:29120
	ds_write_b16_d16_hi v223, v126 offset:29640
	ds_write_b16 v223, v127 offset:30160
	ds_write_b16_d16_hi v223, v127 offset:30680
	ds_write_b16 v223, v128 offset:31200
	ds_write_b16_d16_hi v223, v128 offset:31720
	ds_write_b16 v223, v129 offset:32240
	ds_write_b16_d16_hi v223, v129 offset:32760
	v_mul_f32_e32 v196, 0x3fb8aa3b, v229
	v_cndmask_b32_e64 v196, v207, v196, s[66:67]
	ds_write_b32 v224, v196
	s_waitcnt lgkmcnt(0)
	s_barrier
	s_mov_b32 s2, s13
	s_mov_b64 s[4:5], s[14:15]
	s_mov_b64 s[6:7], s[18:19]
	v_mov_b32_e32 v225, v226
	v_mov_b32_e32 v227, v228
	v_add_u32_e32 v221, s64, v209
	v_add_u32_e32 v222, s65, v216
	s_sub_i32 s64, 0x8200, s64
	s_sub_i32 s65, 0x400, s65
	s_mov_b32 s34, 0
.Lattn_loop:
	s_add_i32 s0, s34, 1
	s_cmp_eq_u32 s45, 0x200
	s_cbranch_scc0 .Lattn_map_old2
	s_lshr_b32 s1, s44, 1
	s_and_b32 s3, s1, 7
	s_lshr_b32 s1, s1, 3
	s_lshl_b32 s63, s3, 3
	s_lshr_b32 s68, s1, 2
	s_add_i32 s63, s63, s68
	s_lshl_b32 s0, s0, 6
	s_add_i32 s63, s63, s0
	s_and_b32 s1, s1, 3
	s_lshl_b32 s1, s1, 1
	s_and_b32 s68, s44, 1
	s_or_b32 s1, s1, s68
	s_lshl_b32 s0, s63, 3
	s_or_b32 s0, s0, s1
	s_branch .Lattn_map_done2

; DI void phase_attn_a(int wv_, int vb_, int nvb_, char* ws_, const Ctx& p, char* smem) {
;     ...
;     const int u = (vb_ + k_ * nvb_ < 6144) ? vb_ + k_ * nvb_ : 6143;
;     const int head = u & 7, g = (u >> 3) % 3, rest = u / 24, idx = rest & 31, b = rest >> 5;
;     const int dil = (g == 0) ? 1 : ((g == 1) ? 4 : 16);
;     const int nbper = 32 / dil, r = idx / nbper, nb = idx % nbper;
;     u16* Og = (g == 0) ? (u16*)(ws_ + WS_H) : ((g == 1) ? (u16*)(ws_ + WS_H + 32 * MiB) : (u16*)(ws_ + WS_E));
;     float* lse = (float*)(ws_ + WS_LSE) + (size_t)g * NTOK * 8;
;     if (tid <= 128) sBias[tid] = p.rel_bias[t5_bucket(tid * dil) * 40 + g * 8 + head] * 1.4426950408889634f;
;     {
;       const int kk = tid; const int ksub = nb * 128 - 128 + kk;
;       bf16x8 v[8];
;       if (ksub >= 0) {
;         const u16* vp = P + ((size_t)b * SEQ + (size_t)ksub * dil + r) * 4608 + 3072 + g * 512 + head * 64;
; #pragma unroll
;         for (int i = 0; i < 8; ++i) v[i] = *(const bf16x8*)(vp + i * 8);
;       } else {
; #pragma unroll
;         for (int i = 0; i < 8; ++i) v[i] = zero8();
;       }
; #pragma unroll
;       for (int i = 0; i < 8; ++i)
; #pragma unroll
;         for (int jj = 0; jj < 8; ++jj) Vt[(i * 8 + jj) * 260 + kk] = (u16)v[i][jj];
;     }
;     __syncthreads();
;     {
;       const int qi = 32 * wave + c;
;       const int qtok = (nb * 128 + qi) * dil + r;
;       const u16* qp = P + ((size_t)b * SEQ + qtok) * 4608 + g * 512 + head * 64;
;       bf16x8 qf[4];
; #pragma unroll
;       for (int ks = 0; ks < 4; ++ks) qf[ks] = *(const bf16x8*)(qp + ks * 16 + h * 8);
.Lattn_map_done2:
	s_min_i32 s0, s0, 0x17ff
	s_and_b32 s1, s0, 7
	s_lshr_b32 s3, s0, 3
	s_mul_hi_u32 s63, s3, 0xaaaaaaab
	s_lshr_b32 s63, s63, 1
	s_mul_i32 s68, s63, 3
	s_sub_i32 s62, s3, s68
	s_and_b32 s69, s63, 31
	s_lshr_b32 s70, s63, 5
	s_lshl_b32 s10, s62, 1
	s_sub_i32 s71, 5, s10
	s_lshr_b32 s11, s69, s71
	s_lshr_b32 s68, 32, s10
	s_add_i32 s68, s68, -1
	s_and_b32 s68, s69, s68
	s_lshl_b32 s12, s68, 7
	s_sub_i32 s71, 4, s60
	s_lshl_b32 s71, 1, s71
	s_add_i32 s71, s71, -1
	s_cmp_eq_u32 s68, 0
	s_cselect_b32 s13, s71, 0
	s_lshl_b32 s71, s62, 3
	s_add_i32 s71, s71, s1
	s_lshl_b32 s100, s71, 22
	s_lshl_b32 s101, s70, 19
	s_add_i32 s100, s100, s101
	s_add_u32 s8, s86, s100
	s_addc_u32 s9, s87, 0
	s_add_u32 s72, s8, 0x6000000
	s_addc_u32 s73, s9, 0
	s_add_u32 s74, s8, 0xc000000
	s_addc_u32 s75, s9, 0
	s_mov_b32 s100, 0x8600000
	s_cmp_eq_u32 s62, 0
	s_cselect_b32 s100, 0x6600000, s100
	s_cmp_eq_u32 s62, 2
	s_cselect_b32 s100, 0x1c600000, s100
	s_lshl_b32 s101, s70, 22
	s_add_i32 s100, s100, s101
	s_lshl_b32 s101, s1, 7
	s_add_i32 s100, s100, s101
	s_add_u32 s14, s78, s100
	s_addc_u32 s15, s79, 0
	s_lshl_b32 s100, s62, 20
	s_lshl_b32 s101, s70, 17
	s_add_i32 s100, s100, s101
	s_lshl_b32 s101, s1, 2
	s_add_i32 s100, s100, s101
	s_add_i32 s100, s100, 0x1e600000
	s_add_u32 s18, s78, s100
	s_addc_u32 s19, s79, 0
	s_lshl_b32 s61, s71, 2
	v_add_u32_e32 v231, s12, v200
	v_lshlrev_b32_e32 v196, s10, v231
	v_add_u32_e32 v196, s11, v196
	v_lshl_add_u32 v226, v196, 10, v239
	v_lshlrev_b32_e32 v228, 5, v196
	v_lshl_add_u32 v232, v196, 7, v201
	v_add_u32_e32 v223, s64, v203
	v_add_u32_e32 v224, s65, v217
	s_cmp_eq_u32 s34, 0
	s_cbranch_scc1 .Lattn_w0
	s_waitcnt vmcnt(9)
	s_branch .Lattn_w1

; #define MFMA32(a, b, c) __builtin_amdgcn_mfma_f32_32x32x16_bf16((a), (b), (c), 0, 0, 0)
; DI float shx(float v, int m) { return __int_as_float(__builtin_amdgcn_ds_bpermute((lane_now() ^ m) << 2, __float_as_int(v))); }
; DI void phase_attn_a(int wv_, int vb_, int nvb_, char* ws_, const Ctx& p, char* smem) {
;     ...
;       for (int kb = 0; kb < 5; ++kb) {
;         const int kk = 32 * wave + 32 * kb + c; const int ksub0 = nb * 128 - 128 + kk;
;         bf16x8 kf[4];
;         if (ksub0 >= 0) {
;           const u16* kp = P + ((size_t)b * SEQ + (size_t)ksub0 * dil + r) * 4608 + 1536 + g * 512 + head * 64;
; #pragma unroll
;           for (int ks = 0; ks < 4; ++ks) kf[ks] = *(const bf16x8*)(kp + ks * 16 + h * 8);
;         } else {
; #pragma unroll
;           for (int ks = 0; ks < 4; ++ks) kf[ks] = zero8();
;         }
;         f32x16 sa = zero16();
; #pragma unroll
;         for (int ks = 0; ks < 4; ++ks) sa = MFMA32(kf[ks], qf[ks], sa);
;         float bm = -INFINITY;
;         const int sbase = c + 128 - 32 * kb - 4 * h;
;         const unsigned slim = (unsigned)((nb * 128 + 32 * wave + c) < 128 ? (nb * 128 + 32 * wave + c) : 128);
;         if (nb > 0 && kb >= 1 && kb <= 3) {
; #pragma unroll
;           for (int i = 0; i < 16; ++i) {
;             const int step = sbase - ((i & 3) + 8 * (i >> 2));
;             const float v = sa[i] + sBias[step];
;             sa[i] = v; bm = fmaxf(bm, v);
;           }
;         } else {
; #pragma unroll
;           for (int i = 0; i < 16; ++i) {
;             const int step = sbase - ((i & 3) + 8 * (i >> 2));
;             const bool valid = (unsigned)step <= slim;
;             const float bv = sBias[step];
;             float v = valid ? sa[i] + bv : -INFINITY;
;             sa[i] = v; bm = fmaxf(bm, v);
;           }
;         }
;         bm = fmaxf(bm, shx(bm, 32));
;         const float mnew = fmaxf(mx, bm);
;         const float mref = (mnew == -INFINITY) ? 0.f : mnew;
;         const float scale = __builtin_amdgcn_exp2f(mx - mref);
;         float ps = 0.f;
; #pragma unroll
;         for (int i = 0; i < 16; ++i) { float pv = __builtin_amdgcn_exp2f(sa[i] - mref); sa[i] = pv; ps += pv; }
;         sum = sum * scale + ps; mx = mnew;
; #pragma unroll
;         for (int i = 0; i < 16; ++i) { oacc[0][i] *= scale; oacc[1][i] *= scale; }
.Lattn_w1:
	v_add_u32_e32 v230, s12, v241
	v_max_i32_e32 v230, 0, v230
	v_lshlrev_b32_e32 v230, s10, v230
	v_add_u32_e32 v230, s11, v230
	v_lshlrev_b32_e32 v230, 7, v230
	global_load_dwordx4 v[98:101], v230, s[74:75]
	global_load_dwordx4 v[102:105], v230, s[74:75] offset:16
	global_load_dwordx4 v[106:109], v230, s[74:75] offset:32
	global_load_dwordx4 v[110:113], v230, s[74:75] offset:48
	global_load_dwordx4 v[114:117], v230, s[74:75] offset:64
	global_load_dwordx4 v[118:121], v230, s[74:75] offset:80
	global_load_dwordx4 v[122:125], v230, s[74:75] offset:96
	global_load_dwordx4 v[126:129], v230, s[74:75] offset:112
	s_cmp_eq_u32 s62, 0
	s_cselect_b64 vcc, -1, 0
	v_cndmask_b32_e32 v196, v219, v218, vcc
	s_cmp_eq_u32 s62, 2
	s_cselect_b64 vcc, -1, 0
	v_cndmask_b32_e32 v196, v196, v220, vcc
	v_add_u32_e32 v196, s61, v196
	global_load_dword v229, v196, s[56:57]
	v_mov_b32_e32 v194, v207
	v_mov_b32_e32 v195, 0
	v_mov_b32_e32 v146, 0
	v_mov_b32_e32 v147, 0
	v_mov_b32_e32 v148, 0
	v_mov_b32_e32 v149, 0
	v_mov_b32_e32 v150, 0
	v_mov_b32_e32 v151, 0
	v_mov_b32_e32 v152, 0
	v_mov_b32_e32 v153, 0
	v_mov_b32_e32 v154, 0
	v_mov_b32_e32 v155, 0
	v_mov_b32_e32 v156, 0
	v_mov_b32_e32 v157, 0
	v_mov_b32_e32 v158, 0
	v_mov_b32_e32 v159, 0
	v_mov_b32_e32 v160, 0
	v_mov_b32_e32 v161, 0
	v_mov_b32_e32 v162, 0
	v_mov_b32_e32 v163, 0
	v_mov_b32_e32 v164, 0
	v_mov_b32_e32 v165, 0
	v_mov_b32_e32 v166, 0
	v_mov_b32_e32 v167, 0
	v_mov_b32_e32 v168, 0
	v_mov_b32_e32 v169, 0
	v_mov_b32_e32 v170, 0
	v_mov_b32_e32 v171, 0
	v_mov_b32_e32 v172, 0
	v_mov_b32_e32 v173, 0
	v_mov_b32_e32 v174, 0
	v_mov_b32_e32 v175, 0
	v_mov_b32_e32 v176, 0
	v_mov_b32_e32 v177, 0
	s_bitcmp1_b32 s2, 0
	s_cbranch_scc1 .Lattn_skip0
	v_mfma_f32_32x32x16_bf16 v[130:145], v[2:5], v[82:85], 0
	v_mfma_f32_32x32x16_bf16 v[130:145], v[6:9], v[86:89], v[130:145]
	v_mfma_f32_32x32x16_bf16 v[130:145], v[10:13], v[90:93], v[130:145]
	v_mfma_f32_32x32x16_bf16 v[130:145], v[14:17], v[94:97], v[130:145]
	v_add_u32_e32 v246, 0xffffff80, v231
	v_max_i32_e32 v246, 0, v246
	v_lshlrev_b32_e32 v246, s10, v246
	v_add_u32_e32 v246, s11, v246
	v_lshl_add_u32 v246, v246, 7, v201
	global_load_dwordx4 v[2:5], v246, s[72:73]
	global_load_dwordx4 v[6:9], v246, s[72:73] offset:32
	global_load_dwordx4 v[10:13], v246, s[72:73] offset:64
	global_load_dwordx4 v[14:17], v246, s[72:73] offset:96
	ds_read2_b32 v[178:179], v222 offset0:159 offset1:158
	ds_read2_b32 v[180:181], v222 offset0:157 offset1:156
	ds_read2_b32 v[182:183], v222 offset0:151 offset1:150
	ds_read2_b32 v[184:185], v222 offset0:149 offset1:148
	ds_read2_b32 v[186:187], v222 offset0:143 offset1:142
	ds_read2_b32 v[188:189], v222 offset0:141 offset1:140
	ds_read2_b32 v[190:191], v222 offset0:135 offset1:134
	ds_read2_b32 v[192:193], v222 offset0:133 offset1:132
	s_nop 0
	s_waitcnt lgkmcnt(0)
	v_add_f32_e32 v130, v130, v178
	v_add_f32_e32 v131, v131, v179
	v_add_f32_e32 v132, v132, v180
	v_add_f32_e32 v133, v133, v181
	v_add_f32_e32 v134, v134, v182
	v_add_f32_e32 v135, v135, v183
	v_add_f32_e32 v136, v136, v184
	v_add_f32_e32 v137, v137, v185
	v_add_f32_e32 v138, v138, v186
	v_add_f32_e32 v139, v139, v187
	v_add_f32_e32 v140, v140, v188
	v_add_f32_e32 v141, v141, v189
	v_add_f32_e32 v142, v142, v190
	v_add_f32_e32 v143, v143, v191
	v_add_f32_e32 v144, v144, v192
	v_add_f32_e32 v145, v145, v193
	ds_read_b64 v[178:179], v221
	ds_read_b64 v[180:181], v221 offset:16
	ds_read_b64 v[182:183], v221 offset:16640
	ds_read_b64 v[184:185], v221 offset:16656
	ds_read_b64 v[186:187], v221 offset:32
	ds_read_b64 v[188:189], v221 offset:48
	ds_read_b64 v[190:191], v221 offset:16672
	ds_read_b64 v[192:193], v221 offset:16688
	v_max3_f32 v235, v130, v131, v132
	v_max3_f32 v235, v235, v133, v134
	v_max3_f32 v235, v235, v135, v136
	v_max3_f32 v235, v235, v137, v138
	v_max3_f32 v235, v235, v139, v140
	v_max3_f32 v235, v235, v141, v142
	v_max3_f32 v235, v235, v143, v144
	v_max_f32_e32 v235, v235, v145
	v_mov_b32_e32 v196, v235
	s_nop 1
	v_permlane32_swap_b32_e32 v196, v235
	v_max_f32_e32 v235, v235, v196
	v_max_f32_e32 v234, v194, v235
	v_cmp_eq_f32_e32 vcc, 0xff800000, v234
	s_nop 1
	v_cndmask_b32_e64 v237, v234, 0, vcc
	v_sub_f32_e32 v196, v194, v237
	v_exp_f32_e32 v233, v196
	v_sub_f32_e32 v130, v130, v237
	v_sub_f32_e32 v131, v131, v237
	v_sub_f32_e32 v132, v132, v237
	v_sub_f32_e32 v133, v133, v237
	v_sub_f32_e32 v134, v134, v237
	v_sub_f32_e32 v135, v135, v237
	v_sub_f32_e32 v136, v136, v237
	v_sub_f32_e32 v137, v137, v237
	v_sub_f32_e32 v138, v138, v237
	v_sub_f32_e32 v139, v139, v237
	v_sub_f32_e32 v140, v140, v237
	v_sub_f32_e32 v141, v141, v237
	v_sub_f32_e32 v142, v142, v237
	v_sub_f32_e32 v143, v143, v237
	v_sub_f32_e32 v144, v144, v237
	v_sub_f32_e32 v145, v145, v237
	v_exp_f32_e32 v130, v130
	v_exp_f32_e32 v131, v131
	v_exp_f32_e32 v132, v132
	v_exp_f32_e32 v133, v133
	v_exp_f32_e32 v134, v134
	v_exp_f32_e32 v135, v135
	v_exp_f32_e32 v136, v136
	v_exp_f32_e32 v137, v137
	v_exp_f32_e32 v138, v138
	v_exp_f32_e32 v139, v139
	v_exp_f32_e32 v140, v140
	v_exp_f32_e32 v141, v141
	v_exp_f32_e32 v142, v142
	v_exp_f32_e32 v143, v143
	v_exp_f32_e32 v144, v144
	v_exp_f32_e32 v145, v145
	v_mov_b32_e32 v194, v234
	v_add_f32_e32 v236, v130, v131
	v_add_f32_e32 v236, v236, v132
	v_add_f32_e32 v236, v236, v133
	v_add_f32_e32 v236, v236, v134
	v_add_f32_e32 v236, v236, v135
	v_add_f32_e32 v236, v236, v136
	v_add_f32_e32 v236, v236, v137
	v_add_f32_e32 v236, v236, v138
	v_add_f32_e32 v236, v236, v139
	v_add_f32_e32 v236, v236, v140
	v_add_f32_e32 v236, v236, v141
	v_add_f32_e32 v236, v236, v142
	v_add_f32_e32 v236, v236, v143
	v_add_f32_e32 v236, v236, v144
	v_add_f32_e32 v236, v236, v145
	v_fma_f32 v195, v195, v233, v236
	v_mul_f32_e32 v146, v233, v146
	v_mul_f32_e32 v147, v233, v147
	v_mul_f32_e32 v148, v233, v148
	v_mul_f32_e32 v149, v233, v149
	v_mul_f32_e32 v150, v233, v150
	v_mul_f32_e32 v151, v233, v151
	v_mul_f32_e32 v152, v233, v152
	v_mul_f32_e32 v153, v233, v153
	v_mul_f32_e32 v154, v233, v154
	v_mul_f32_e32 v155, v233, v155
	v_mul_f32_e32 v156, v233, v156
	v_mul_f32_e32 v157, v233, v157
	v_mul_f32_e32 v158, v233, v158
	v_mul_f32_e32 v159, v233, v159
	v_mul_f32_e32 v160, v233, v160
	v_mul_f32_e32 v161, v233, v161
	v_mul_f32_e32 v162, v233, v162
	v_mul_f32_e32 v163, v233, v163
	v_mul_f32_e32 v164, v233, v164
	v_mul_f32_e32 v165, v233, v165
	v_mul_f32_e32 v166, v233, v166
	v_mul_f32_e32 v167, v233, v167
	v_mul_f32_e32 v168, v233, v168
	v_mul_f32_e32 v169, v233, v169
	v_mul_f32_e32 v170, v233, v170
	v_mul_f32_e32 v171, v233, v171
	v_mul_f32_e32 v172, v233, v172
	v_mul_f32_e32 v173, v233, v173
	v_mul_f32_e32 v174, v233, v174
	v_mul_f32_e32 v175, v233, v175
	v_mul_f32_e32 v176, v233, v176
	v_mul_f32_e32 v177, v233, v177
	v_cvt_pk_bf16_f32 v130, v130, v131
	v_cvt_pk_bf16_f32 v131, v132, v133
	v_cvt_pk_bf16_f32 v132, v134, v135
	v_cvt_pk_bf16_f32 v133, v136, v137
	v_cvt_pk_bf16_f32 v134, v138, v139
	v_cvt_pk_bf16_f32 v135, v140, v141
	v_cvt_pk_bf16_f32 v136, v142, v143
	v_cvt_pk_bf16_f32 v137, v144, v145
	s_waitcnt lgkmcnt(0)
; DI void phase_attn_a(int wv_, int vb_, int nvb_, char* ws_, const Ctx& p, char* smem) {
;     ...
;       for (int kb = 0; kb < 5; ++kb) {
;         const int kk = 32 * wave + 32 * kb + c; const int ksub0 = nb * 128 - 128 + kk;
;         bf16x8 kf[4];
;         if (ksub0 >= 0) {
;           const u16* kp = P + ((size_t)b * SEQ + (size_t)ksub0 * dil + r) * 4608 + 1536 + g * 512 + head * 64;
; #pragma unroll
;           for (int ks = 0; ks < 4; ++ks) kf[ks] = *(const bf16x8*)(kp + ks * 16 + h * 8);
;         } else {
; #pragma unroll
;           for (int ks = 0; ks < 4; ++ks) kf[ks] = zero8();
;         }
;         f32x16 sa = zero16();
; #pragma unroll
;         for (int ks = 0; ks < 4; ++ks) sa = MFMA32(kf[ks], qf[ks], sa);
;         float bm = -INFINITY;
;         const int sbase = c + 128 - 32 * kb - 4 * h;
;         const unsigned slim = (unsigned)((nb * 128 + 32 * wave + c) < 128 ? (nb * 128 + 32 * wave + c) : 128);
;         if (nb > 0 && kb >= 1 && kb <= 3) {
; #pragma unroll
;           for (int i = 0; i < 16; ++i) {
;             const int step = sbase - ((i & 3) + 8 * (i >> 2));
;             const float v = sa[i] + sBias[step];
;             sa[i] = v; bm = fmaxf(bm, v);
;           }
;         } else {
; #pragma unroll
;           for (int i = 0; i < 16; ++i) {
;             const int step = sbase - ((i & 3) + 8 * (i >> 2));
;             const bool valid = (unsigned)step <= slim;
;             const float bv = sBias[step];
;             float v = valid ? sa[i] + bv : -INFINITY;
;             sa[i] = v; bm = fmaxf(bm, v);
;           }
;         }
;         bm = fmaxf(bm, shx(bm, 32));
;         const float mnew = fmaxf(mx, bm);
;         const float mref = (mnew == -INFINITY) ? 0.f : mnew;
;         const float scale = __builtin_amdgcn_exp2f(mx - mref);
;         float ps = 0.f;
; #pragma unroll
;         for (int i = 0; i < 16; ++i) { float pv = __builtin_amdgcn_exp2f(sa[i] - mref); sa[i] = pv; ps += pv; }
;         sum = sum * scale + ps; mx = mnew;
; #pragma unroll
;         for (int i = 0; i < 16; ++i) { oacc[0][i] *= scale; oacc[1][i] *= scale; }
; #pragma unroll
;         for (int s = 0; s < 2; ++s) {
;           bf16x8 pb = pack8(sa, s);
;           const int keybase = 32 * wave + 32 * kb + 16 * s;
; #pragma unroll
;           for (int mb = 0; mb < 2; ++mb) {
;             const u16* vr = Vt + (mb * 32 + c) * 260 + keybase + 4 * h;
	s_nop 1
	v_mfma_f32_32x32x16_bf16 v[146:161], v[178:181], v[130:133], v[146:161]
	v_mfma_f32_32x32x16_bf16 v[162:177], v[182:185], v[130:133], v[162:177]
	v_mfma_f32_32x32x16_bf16 v[146:161], v[186:189], v[134:137], v[146:161]
	v_mfma_f32_32x32x16_bf16 v[162:177], v[190:193], v[134:137], v[162:177]
	s_branch .Lattn_end0
.Lattn_skip0:
	v_add_u32_e32 v246, 0xffffff80, v231
	v_max_i32_e32 v246, 0, v246
	v_lshlrev_b32_e32 v246, s10, v246
	v_add_u32_e32 v246, s11, v246
	v_lshl_add_u32 v246, v246, 7, v201
	global_load_dwordx4 v[2:5], v246, s[72:73]
	global_load_dwordx4 v[6:9], v246, s[72:73] offset:32
	global_load_dwordx4 v[10:13], v246, s[72:73] offset:64
	global_load_dwordx4 v[14:17], v246, s[72:73] offset:96
.Lattn_end0:
	s_bitcmp1_b32 s2, 1
	s_cbranch_scc1 .Lattn_skip1
	v_mfma_f32_32x32x16_bf16 v[130:145], v[18:21], v[82:85], 0
	v_mfma_f32_32x32x16_bf16 v[130:145], v[22:25], v[86:89], v[130:145]
	v_mfma_f32_32x32x16_bf16 v[130:145], v[26:29], v[90:93], v[130:145]
	v_mfma_f32_32x32x16_bf16 v[130:145], v[30:33], v[94:97], v[130:145]
	v_add_u32_e32 v246, 0xffffffa0, v231
	v_max_i32_e32 v246, 0, v246
	v_lshlrev_b32_e32 v246, s10, v246
	v_add_u32_e32 v246, s11, v246
	v_lshl_add_u32 v246, v246, 7, v201
	global_load_dwordx4 v[18:21], v246, s[72:73]
	global_load_dwordx4 v[22:25], v246, s[72:73] offset:32
	global_load_dwordx4 v[26:29], v246, s[72:73] offset:64
	global_load_dwordx4 v[30:33], v246, s[72:73] offset:96
	ds_read2_b32 v[178:179], v222 offset0:127 offset1:126
	ds_read2_b32 v[180:181], v222 offset0:125 offset1:124
	ds_read2_b32 v[182:183], v222 offset0:119 offset1:118
	ds_read2_b32 v[184:185], v222 offset0:117 offset1:116
	ds_read2_b32 v[186:187], v222 offset0:111 offset1:110
	ds_read2_b32 v[188:189], v222 offset0:109 offset1:108
	ds_read2_b32 v[190:191], v222 offset0:103 offset1:102
	ds_read2_b32 v[192:193], v222 offset0:101 offset1:100
	s_nop 0
	s_waitcnt lgkmcnt(0)
	v_add_f32_e32 v130, v130, v178
	v_add_f32_e32 v131, v131, v179
	v_add_f32_e32 v132, v132, v180
	v_add_f32_e32 v133, v133, v181
	v_add_f32_e32 v134, v134, v182
	v_add_f32_e32 v135, v135, v183
	v_add_f32_e32 v136, v136, v184
	v_add_f32_e32 v137, v137, v185
	v_add_f32_e32 v138, v138, v186
	v_add_f32_e32 v139, v139, v187
	v_add_f32_e32 v140, v140, v188
	v_add_f32_e32 v141, v141, v189
	v_add_f32_e32 v142, v142, v190
	v_add_f32_e32 v143, v143, v191
	v_add_f32_e32 v144, v144, v192
	v_add_f32_e32 v145, v145, v193
	ds_read_b64 v[178:179], v221 offset:64
	ds_read_b64 v[180:181], v221 offset:80
	ds_read_b64 v[182:183], v221 offset:16704
	ds_read_b64 v[184:185], v221 offset:16720
	ds_read_b64 v[186:187], v221 offset:96
	ds_read_b64 v[188:189], v221 offset:112
	ds_read_b64 v[190:191], v221 offset:16736
	ds_read_b64 v[192:193], v221 offset:16752
	v_max3_f32 v235, v130, v131, v132
	v_max3_f32 v235, v235, v133, v134
	v_max3_f32 v235, v235, v135, v136
	v_max3_f32 v235, v235, v137, v138
	v_max3_f32 v235, v235, v139, v140
	v_max3_f32 v235, v235, v141, v142
	v_max3_f32 v235, v235, v143, v144
	v_max_f32_e32 v235, v235, v145
	v_mov_b32_e32 v196, v235
	s_nop 1
	v_permlane32_swap_b32_e32 v196, v235
	v_max_f32_e32 v235, v235, v196
	v_max_f32_e32 v234, v194, v235
	v_cmp_eq_f32_e32 vcc, 0xff800000, v234
	s_nop 1
	v_cndmask_b32_e64 v237, v234, 0, vcc
	v_sub_f32_e32 v196, v194, v237
	v_exp_f32_e32 v233, v196
	v_sub_f32_e32 v130, v130, v237
	v_sub_f32_e32 v131, v131, v237
	v_sub_f32_e32 v132, v132, v237
	v_sub_f32_e32 v133, v133, v237
	v_sub_f32_e32 v134, v134, v237
	v_sub_f32_e32 v135, v135, v237
	v_sub_f32_e32 v136, v136, v237
	v_sub_f32_e32 v137, v137, v237
	v_sub_f32_e32 v138, v138, v237
	v_sub_f32_e32 v139, v139, v237
	v_sub_f32_e32 v140, v140, v237
	v_sub_f32_e32 v141, v141, v237
	v_sub_f32_e32 v142, v142, v237
	v_sub_f32_e32 v143, v143, v237
	v_sub_f32_e32 v144, v144, v237
	v_sub_f32_e32 v145, v145, v237
	v_exp_f32_e32 v130, v130
	v_exp_f32_e32 v131, v131
	v_exp_f32_e32 v132, v132
	v_exp_f32_e32 v133, v133
	v_exp_f32_e32 v134, v134
	v_exp_f32_e32 v135, v135
	v_exp_f32_e32 v136, v136
	v_exp_f32_e32 v137, v137
	v_exp_f32_e32 v138, v138
	v_exp_f32_e32 v139, v139
	v_exp_f32_e32 v140, v140
	v_exp_f32_e32 v141, v141
	v_exp_f32_e32 v142, v142
	v_exp_f32_e32 v143, v143
	v_exp_f32_e32 v144, v144
	v_exp_f32_e32 v145, v145
	v_mov_b32_e32 v194, v234
	v_add_f32_e32 v236, v130, v131
	v_add_f32_e32 v236, v236, v132
	v_add_f32_e32 v236, v236, v133
	v_add_f32_e32 v236, v236, v134
	v_add_f32_e32 v236, v236, v135
	v_add_f32_e32 v236, v236, v136
	v_add_f32_e32 v236, v236, v137
	v_add_f32_e32 v236, v236, v138
	v_add_f32_e32 v236, v236, v139
	v_add_f32_e32 v236, v236, v140
	v_add_f32_e32 v236, v236, v141
	v_add_f32_e32 v236, v236, v142
	v_add_f32_e32 v236, v236, v143
	v_add_f32_e32 v236, v236, v144
	v_add_f32_e32 v236, v236, v145
	v_fma_f32 v195, v195, v233, v236
	v_mul_f32_e32 v146, v233, v146
	v_mul_f32_e32 v147, v233, v147
	v_mul_f32_e32 v148, v233, v148
	v_mul_f32_e32 v149, v233, v149
	v_mul_f32_e32 v150, v233, v150
	v_mul_f32_e32 v151, v233, v151
	v_mul_f32_e32 v152, v233, v152
	v_mul_f32_e32 v153, v233, v153
	v_mul_f32_e32 v154, v233, v154
	v_mul_f32_e32 v155, v233, v155
	v_mul_f32_e32 v156, v233, v156
	v_mul_f32_e32 v157, v233, v157
	v_mul_f32_e32 v158, v233, v158
	v_mul_f32_e32 v159, v233, v159
	v_mul_f32_e32 v160, v233, v160
	v_mul_f32_e32 v161, v233, v161
	v_mul_f32_e32 v162, v233, v162
	v_mul_f32_e32 v163, v233, v163
	v_mul_f32_e32 v164, v233, v164
	v_mul_f32_e32 v165, v233, v165
	v_mul_f32_e32 v166, v233, v166
	v_mul_f32_e32 v167, v233, v167
	v_mul_f32_e32 v168, v233, v168
	v_mul_f32_e32 v169, v233, v169
	v_mul_f32_e32 v170, v233, v170
	v_mul_f32_e32 v171, v233, v171
	v_mul_f32_e32 v172, v233, v172
	v_mul_f32_e32 v173, v233, v173
	v_mul_f32_e32 v174, v233, v174
	v_mul_f32_e32 v175, v233, v175
	v_mul_f32_e32 v176, v233, v176
	v_mul_f32_e32 v177, v233, v177
	v_cvt_pk_bf16_f32 v130, v130, v131
	v_cvt_pk_bf16_f32 v131, v132, v133
	v_cvt_pk_bf16_f32 v132, v134, v135
	v_cvt_pk_bf16_f32 v133, v136, v137
	v_cvt_pk_bf16_f32 v134, v138, v139
	v_cvt_pk_bf16_f32 v135, v140, v141
	v_cvt_pk_bf16_f32 v136, v142, v143
	v_cvt_pk_bf16_f32 v137, v144, v145
	s_waitcnt lgkmcnt(0)
	s_nop 1
	v_mfma_f32_32x32x16_bf16 v[146:161], v[178:181], v[130:133], v[146:161]
	v_mfma_f32_32x32x16_bf16 v[162:177], v[182:185], v[130:133], v[162:177]
	v_mfma_f32_32x32x16_bf16 v[146:161], v[186:189], v[134:137], v[146:161]
	v_mfma_f32_32x32x16_bf16 v[162:177], v[190:193], v[134:137], v[162:177]
	s_branch .Lattn_end1
; DI void phase_attn_a(int wv_, int vb_, int nvb_, char* ws_, const Ctx& p, char* smem) {
;     ...
;       for (int kb = 0; kb < 5; ++kb) {
;         const int kk = 32 * wave + 32 * kb + c; const int ksub0 = nb * 128 - 128 + kk;
;         bf16x8 kf[4];
;         if (ksub0 >= 0) {
;           const u16* kp = P + ((size_t)b * SEQ + (size_t)ksub0 * dil + r) * 4608 + 1536 + g * 512 + head * 64;
; #pragma unroll
;           for (int ks = 0; ks < 4; ++ks) kf[ks] = *(const bf16x8*)(kp + ks * 16 + h * 8);
;         } else {
; #pragma unroll
;           for (int ks = 0; ks < 4; ++ks) kf[ks] = zero8();
;         }
;         f32x16 sa = zero16();
; #pragma unroll
;         for (int ks = 0; ks < 4; ++ks) sa = MFMA32(kf[ks], qf[ks], sa);
;         float bm = -INFINITY;
;         const int sbase = c + 128 - 32 * kb - 4 * h;
;         const unsigned slim = (unsigned)((nb * 128 + 32 * wave + c) < 128 ? (nb * 128 + 32 * wave + c) : 128);
;         if (nb > 0 && kb >= 1 && kb <= 3) {
; #pragma unroll
;           for (int i = 0; i < 16; ++i) {
;             const int step = sbase - ((i & 3) + 8 * (i >> 2));
;             const float v = sa[i] + sBias[step];
;             sa[i] = v; bm = fmaxf(bm, v);
;           }
;         } else {
; #pragma unroll
;           for (int i = 0; i < 16; ++i) {
;             const int step = sbase - ((i & 3) + 8 * (i >> 2));
;             const bool valid = (unsigned)step <= slim;
;             const float bv = sBias[step];
;             float v = valid ? sa[i] + bv : -INFINITY;
;             sa[i] = v; bm = fmaxf(bm, v);
;           }
;         }
;         bm = fmaxf(bm, shx(bm, 32));
;         const float mnew = fmaxf(mx, bm);
;         const float mref = (mnew == -INFINITY) ? 0.f : mnew;
;         const float scale = __builtin_amdgcn_exp2f(mx - mref);
;         float ps = 0.f;
; #pragma unroll
;         for (int i = 0; i < 16; ++i) { float pv = __builtin_amdgcn_exp2f(sa[i] - mref); sa[i] = pv; ps += pv; }
;         sum = sum * scale + ps; mx = mnew;
; #pragma unroll
;         for (int i = 0; i < 16; ++i) { oacc[0][i] *= scale; oacc[1][i] *= scale; }
; #pragma unroll
;         for (int s = 0; s < 2; ++s) {
;           bf16x8 pb = pack8(sa, s);
;           const int keybase = 32 * wave + 32 * kb + 16 * s;
; #pragma unroll
;           for (int mb = 0; mb < 2; ++mb) {
;             const u16* vr = Vt + (mb * 32 + c) * 260 + keybase + 4 * h;
.Lattn_skip1:
	v_add_u32_e32 v246, 0xffffffa0, v231
	v_max_i32_e32 v246, 0, v246
	v_lshlrev_b32_e32 v246, s10, v246
	v_add_u32_e32 v246, s11, v246
	v_lshl_add_u32 v246, v246, 7, v201
	global_load_dwordx4 v[18:21], v246, s[72:73]
	global_load_dwordx4 v[22:25], v246, s[72:73] offset:32
	global_load_dwordx4 v[26:29], v246, s[72:73] offset:64
	global_load_dwordx4 v[30:33], v246, s[72:73] offset:96
.Lattn_end1:
	s_bitcmp1_b32 s2, 2
	s_cbranch_scc1 .Lattn_skip2
	v_mfma_f32_32x32x16_bf16 v[130:145], v[34:37], v[82:85], 0
	v_mfma_f32_32x32x16_bf16 v[130:145], v[38:41], v[86:89], v[130:145]
	v_mfma_f32_32x32x16_bf16 v[130:145], v[42:45], v[90:93], v[130:145]
	v_mfma_f32_32x32x16_bf16 v[130:145], v[46:49], v[94:97], v[130:145]
	v_add_u32_e32 v246, 0xffffffc0, v231
	v_max_i32_e32 v246, 0, v246
	v_lshlrev_b32_e32 v246, s10, v246
	v_add_u32_e32 v246, s11, v246
	v_lshl_add_u32 v246, v246, 7, v201
	global_load_dwordx4 v[34:37], v246, s[72:73]
	global_load_dwordx4 v[38:41], v246, s[72:73] offset:32
	global_load_dwordx4 v[42:45], v246, s[72:73] offset:64
	global_load_dwordx4 v[46:49], v246, s[72:73] offset:96
	ds_read2_b32 v[178:179], v222 offset0:95 offset1:94
	ds_read2_b32 v[180:181], v222 offset0:93 offset1:92
	ds_read2_b32 v[182:183], v222 offset0:87 offset1:86
	ds_read2_b32 v[184:185], v222 offset0:85 offset1:84
	ds_read2_b32 v[186:187], v222 offset0:79 offset1:78
	ds_read2_b32 v[188:189], v222 offset0:77 offset1:76
	ds_read2_b32 v[190:191], v222 offset0:71 offset1:70
	ds_read2_b32 v[192:193], v222 offset0:69 offset1:68
	s_nop 0
	s_waitcnt lgkmcnt(0)
	v_add_f32_e32 v130, v130, v178
	v_add_f32_e32 v131, v131, v179
	v_add_f32_e32 v132, v132, v180
	v_add_f32_e32 v133, v133, v181
	v_add_f32_e32 v134, v134, v182
	v_add_f32_e32 v135, v135, v183
	v_add_f32_e32 v136, v136, v184
	v_add_f32_e32 v137, v137, v185
	v_add_f32_e32 v138, v138, v186
	v_add_f32_e32 v139, v139, v187
	v_add_f32_e32 v140, v140, v188
	v_add_f32_e32 v141, v141, v189
	v_add_f32_e32 v142, v142, v190
	v_add_f32_e32 v143, v143, v191
	v_add_f32_e32 v144, v144, v192
	v_add_f32_e32 v145, v145, v193
	ds_read_b64 v[178:179], v221 offset:128
	ds_read_b64 v[180:181], v221 offset:144
	ds_read_b64 v[182:183], v221 offset:16768
	ds_read_b64 v[184:185], v221 offset:16784
	ds_read_b64 v[186:187], v221 offset:160
	ds_read_b64 v[188:189], v221 offset:176
	ds_read_b64 v[190:191], v221 offset:16800
	ds_read_b64 v[192:193], v221 offset:16816
	v_max3_f32 v235, v130, v131, v132
	v_max3_f32 v235, v235, v133, v134
	v_max3_f32 v235, v235, v135, v136
	v_max3_f32 v235, v235, v137, v138
	v_max3_f32 v235, v235, v139, v140
	v_max3_f32 v235, v235, v141, v142
	v_max3_f32 v235, v235, v143, v144
	v_max_f32_e32 v235, v235, v145
	v_mov_b32_e32 v196, v235
	s_nop 1
	v_permlane32_swap_b32_e32 v196, v235
	v_max_f32_e32 v235, v235, v196
	v_max_f32_e32 v234, v194, v235
	v_cmp_eq_f32_e32 vcc, 0xff800000, v234
	s_nop 1
	v_cndmask_b32_e64 v237, v234, 0, vcc
	v_sub_f32_e32 v196, v194, v237
	v_exp_f32_e32 v233, v196
	v_sub_f32_e32 v130, v130, v237
	v_sub_f32_e32 v131, v131, v237
	v_sub_f32_e32 v132, v132, v237
	v_sub_f32_e32 v133, v133, v237
	v_sub_f32_e32 v134, v134, v237
	v_sub_f32_e32 v135, v135, v237
	v_sub_f32_e32 v136, v136, v237
	v_sub_f32_e32 v137, v137, v237
	v_sub_f32_e32 v138, v138, v237
	v_sub_f32_e32 v139, v139, v237
	v_sub_f32_e32 v140, v140, v237
	v_sub_f32_e32 v141, v141, v237
	v_sub_f32_e32 v142, v142, v237
	v_sub_f32_e32 v143, v143, v237
	v_sub_f32_e32 v144, v144, v237
	v_sub_f32_e32 v145, v145, v237
	v_exp_f32_e32 v130, v130
	v_exp_f32_e32 v131, v131
	v_exp_f32_e32 v132, v132
	v_exp_f32_e32 v133, v133
	v_exp_f32_e32 v134, v134
	v_exp_f32_e32 v135, v135
	v_exp_f32_e32 v136, v136
	v_exp_f32_e32 v137, v137
	v_exp_f32_e32 v138, v138
	v_exp_f32_e32 v139, v139
	v_exp_f32_e32 v140, v140
	v_exp_f32_e32 v141, v141
	v_exp_f32_e32 v142, v142
	v_exp_f32_e32 v143, v143
	v_exp_f32_e32 v144, v144
	v_exp_f32_e32 v145, v145
	v_mov_b32_e32 v194, v234
	v_add_f32_e32 v236, v130, v131
	v_add_f32_e32 v236, v236, v132
	v_add_f32_e32 v236, v236, v133
	v_add_f32_e32 v236, v236, v134
	v_add_f32_e32 v236, v236, v135
	v_add_f32_e32 v236, v236, v136
	v_add_f32_e32 v236, v236, v137
	v_add_f32_e32 v236, v236, v138
	v_add_f32_e32 v236, v236, v139
	v_add_f32_e32 v236, v236, v140
	v_add_f32_e32 v236, v236, v141
	v_add_f32_e32 v236, v236, v142
	v_add_f32_e32 v236, v236, v143
	v_add_f32_e32 v236, v236, v144
	v_add_f32_e32 v236, v236, v145
	v_fma_f32 v195, v195, v233, v236
	v_mul_f32_e32 v146, v233, v146
	v_mul_f32_e32 v147, v233, v147
	v_mul_f32_e32 v148, v233, v148
	v_mul_f32_e32 v149, v233, v149
	v_mul_f32_e32 v150, v233, v150
	v_mul_f32_e32 v151, v233, v151
	v_mul_f32_e32 v152, v233, v152
	v_mul_f32_e32 v153, v233, v153
	v_mul_f32_e32 v154, v233, v154
	v_mul_f32_e32 v155, v233, v155
	v_mul_f32_e32 v156, v233, v156
	v_mul_f32_e32 v157, v233, v157
	v_mul_f32_e32 v158, v233, v158
	v_mul_f32_e32 v159, v233, v159
	v_mul_f32_e32 v160, v233, v160
	v_mul_f32_e32 v161, v233, v161
	v_mul_f32_e32 v162, v233, v162
	v_mul_f32_e32 v163, v233, v163
	v_mul_f32_e32 v164, v233, v164
	v_mul_f32_e32 v165, v233, v165
	v_mul_f32_e32 v166, v233, v166
	v_mul_f32_e32 v167, v233, v167
	v_mul_f32_e32 v168, v233, v168
	v_mul_f32_e32 v169, v233, v169
	v_mul_f32_e32 v170, v233, v170
	v_mul_f32_e32 v171, v233, v171
	v_mul_f32_e32 v172, v233, v172
	v_mul_f32_e32 v173, v233, v173
	v_mul_f32_e32 v174, v233, v174
	v_mul_f32_e32 v175, v233, v175
	v_mul_f32_e32 v176, v233, v176
	v_mul_f32_e32 v177, v233, v177
	v_cvt_pk_bf16_f32 v130, v130, v131
	v_cvt_pk_bf16_f32 v131, v132, v133
	v_cvt_pk_bf16_f32 v132, v134, v135
	v_cvt_pk_bf16_f32 v133, v136, v137
	v_cvt_pk_bf16_f32 v134, v138, v139
	v_cvt_pk_bf16_f32 v135, v140, v141
	v_cvt_pk_bf16_f32 v136, v142, v143
	v_cvt_pk_bf16_f32 v137, v144, v145
	s_waitcnt lgkmcnt(0)
	s_nop 1
	v_mfma_f32_32x32x16_bf16 v[146:161], v[178:181], v[130:133], v[146:161]
	v_mfma_f32_32x32x16_bf16 v[162:177], v[182:185], v[130:133], v[162:177]
	v_mfma_f32_32x32x16_bf16 v[146:161], v[186:189], v[134:137], v[146:161]
	v_mfma_f32_32x32x16_bf16 v[162:177], v[190:193], v[134:137], v[162:177]
	s_branch .Lattn_end2
; DI void phase_attn_a(int wv_, int vb_, int nvb_, char* ws_, const Ctx& p, char* smem) {
;     ...
;       for (int kb = 0; kb < 5; ++kb) {
;         const int kk = 32 * wave + 32 * kb + c; const int ksub0 = nb * 128 - 128 + kk;
;         bf16x8 kf[4];
;         if (ksub0 >= 0) {
;           const u16* kp = P + ((size_t)b * SEQ + (size_t)ksub0 * dil + r) * 4608 + 1536 + g * 512 + head * 64;
; #pragma unroll
;           for (int ks = 0; ks < 4; ++ks) kf[ks] = *(const bf16x8*)(kp + ks * 16 + h * 8);
;         } else {
; #pragma unroll
;           for (int ks = 0; ks < 4; ++ks) kf[ks] = zero8();
;         }
;         f32x16 sa = zero16();
; #pragma unroll
;         for (int ks = 0; ks < 4; ++ks) sa = MFMA32(kf[ks], qf[ks], sa);
;         float bm = -INFINITY;
;         const int sbase = c + 128 - 32 * kb - 4 * h;
;         const unsigned slim = (unsigned)((nb * 128 + 32 * wave + c) < 128 ? (nb * 128 + 32 * wave + c) : 128);
;         if (nb > 0 && kb >= 1 && kb <= 3) {
; #pragma unroll
;           for (int i = 0; i < 16; ++i) {
;             const int step = sbase - ((i & 3) + 8 * (i >> 2));
;             const float v = sa[i] + sBias[step];
;             sa[i] = v; bm = fmaxf(bm, v);
;           }
;         } else {
; #pragma unroll
;           for (int i = 0; i < 16; ++i) {
;             const int step = sbase - ((i & 3) + 8 * (i >> 2));
;             const bool valid = (unsigned)step <= slim;
;             const float bv = sBias[step];
;             float v = valid ? sa[i] + bv : -INFINITY;
;             sa[i] = v; bm = fmaxf(bm, v);
;           }
;         }
;         bm = fmaxf(bm, shx(bm, 32));
;         const float mnew = fmaxf(mx, bm);
;         const float mref = (mnew == -INFINITY) ? 0.f : mnew;
;         const float scale = __builtin_amdgcn_exp2f(mx - mref);
;         float ps = 0.f;
; #pragma unroll
;         for (int i = 0; i < 16; ++i) { float pv = __builtin_amdgcn_exp2f(sa[i] - mref); sa[i] = pv; ps += pv; }
;         sum = sum * scale + ps; mx = mnew;
; #pragma unroll
;         for (int i = 0; i < 16; ++i) { oacc[0][i] *= scale; oacc[1][i] *= scale; }
; #pragma unroll
;         for (int s = 0; s < 2; ++s) {
;           bf16x8 pb = pack8(sa, s);
;           const int keybase = 32 * wave + 32 * kb + 16 * s;
; #pragma unroll
;           for (int mb = 0; mb < 2; ++mb) {
;             const u16* vr = Vt + (mb * 32 + c) * 260 + keybase + 4 * h;
.Lattn_skip2:
	v_add_u32_e32 v246, 0xffffffc0, v231
	v_max_i32_e32 v246, 0, v246
	v_lshlrev_b32_e32 v246, s10, v246
	v_add_u32_e32 v246, s11, v246
	v_lshl_add_u32 v246, v246, 7, v201
	global_load_dwordx4 v[34:37], v246, s[72:73]
	global_load_dwordx4 v[38:41], v246, s[72:73] offset:32
	global_load_dwordx4 v[42:45], v246, s[72:73] offset:64
	global_load_dwordx4 v[46:49], v246, s[72:73] offset:96
.Lattn_end2:
	s_bitcmp1_b32 s2, 3
	s_cbranch_scc1 .Lattn_skip3
	v_mfma_f32_32x32x16_bf16 v[130:145], v[50:53], v[82:85], 0
	v_mfma_f32_32x32x16_bf16 v[130:145], v[54:57], v[86:89], v[130:145]
	v_mfma_f32_32x32x16_bf16 v[130:145], v[58:61], v[90:93], v[130:145]
	v_mfma_f32_32x32x16_bf16 v[130:145], v[62:65], v[94:97], v[130:145]
	v_add_u32_e32 v246, 0xffffffe0, v231
	v_max_i32_e32 v246, 0, v246
	v_lshlrev_b32_e32 v246, s10, v246
	v_add_u32_e32 v246, s11, v246
	v_lshl_add_u32 v246, v246, 7, v201
	global_load_dwordx4 v[50:53], v246, s[72:73]
	global_load_dwordx4 v[54:57], v246, s[72:73] offset:32
	global_load_dwordx4 v[58:61], v246, s[72:73] offset:64
	global_load_dwordx4 v[62:65], v246, s[72:73] offset:96
	ds_read2_b32 v[178:179], v222 offset0:63 offset1:62
	ds_read2_b32 v[180:181], v222 offset0:61 offset1:60
	ds_read2_b32 v[182:183], v222 offset0:55 offset1:54
	ds_read2_b32 v[184:185], v222 offset0:53 offset1:52
	ds_read2_b32 v[186:187], v222 offset0:47 offset1:46
	ds_read2_b32 v[188:189], v222 offset0:45 offset1:44
	ds_read2_b32 v[190:191], v222 offset0:39 offset1:38
	ds_read2_b32 v[192:193], v222 offset0:37 offset1:36
	s_nop 0
	s_waitcnt lgkmcnt(0)
	v_add_f32_e32 v130, v130, v178
	v_add_f32_e32 v131, v131, v179
	v_add_f32_e32 v132, v132, v180
	v_add_f32_e32 v133, v133, v181
	v_add_f32_e32 v134, v134, v182
	v_add_f32_e32 v135, v135, v183
	v_add_f32_e32 v136, v136, v184
	v_add_f32_e32 v137, v137, v185
	v_add_f32_e32 v138, v138, v186
	v_add_f32_e32 v139, v139, v187
	v_add_f32_e32 v140, v140, v188
	v_add_f32_e32 v141, v141, v189
	v_add_f32_e32 v142, v142, v190
	v_add_f32_e32 v143, v143, v191
	v_add_f32_e32 v144, v144, v192
	v_add_f32_e32 v145, v145, v193
	ds_read_b64 v[178:179], v221 offset:192
	ds_read_b64 v[180:181], v221 offset:208
	ds_read_b64 v[182:183], v221 offset:16832
	ds_read_b64 v[184:185], v221 offset:16848
	ds_read_b64 v[186:187], v221 offset:224
	ds_read_b64 v[188:189], v221 offset:240
	ds_read_b64 v[190:191], v221 offset:16864
	ds_read_b64 v[192:193], v221 offset:16880
	v_max3_f32 v235, v130, v131, v132
	v_max3_f32 v235, v235, v133, v134
	v_max3_f32 v235, v235, v135, v136
	v_max3_f32 v235, v235, v137, v138
	v_max3_f32 v235, v235, v139, v140
	v_max3_f32 v235, v235, v141, v142
	v_max3_f32 v235, v235, v143, v144
	v_max_f32_e32 v235, v235, v145
	v_mov_b32_e32 v196, v235
	s_nop 1
	v_permlane32_swap_b32_e32 v196, v235
	v_max_f32_e32 v235, v235, v196
	v_max_f32_e32 v234, v194, v235
	v_cmp_eq_f32_e32 vcc, 0xff800000, v234
	s_nop 1
	v_cndmask_b32_e64 v237, v234, 0, vcc
	v_sub_f32_e32 v196, v194, v237
	v_exp_f32_e32 v233, v196
	v_sub_f32_e32 v130, v130, v237
	v_sub_f32_e32 v131, v131, v237
	v_sub_f32_e32 v132, v132, v237
	v_sub_f32_e32 v133, v133, v237
	v_sub_f32_e32 v134, v134, v237
	v_sub_f32_e32 v135, v135, v237
	v_sub_f32_e32 v136, v136, v237
	v_sub_f32_e32 v137, v137, v237
	v_sub_f32_e32 v138, v138, v237
	v_sub_f32_e32 v139, v139, v237
	v_sub_f32_e32 v140, v140, v237
	v_sub_f32_e32 v141, v141, v237
	v_sub_f32_e32 v142, v142, v237
	v_sub_f32_e32 v143, v143, v237
	v_sub_f32_e32 v144, v144, v237
	v_sub_f32_e32 v145, v145, v237
	v_exp_f32_e32 v130, v130
	v_exp_f32_e32 v131, v131
	v_exp_f32_e32 v132, v132
	v_exp_f32_e32 v133, v133
	v_exp_f32_e32 v134, v134
	v_exp_f32_e32 v135, v135
	v_exp_f32_e32 v136, v136
	v_exp_f32_e32 v137, v137
	v_exp_f32_e32 v138, v138
	v_exp_f32_e32 v139, v139
	v_exp_f32_e32 v140, v140
	v_exp_f32_e32 v141, v141
	v_exp_f32_e32 v142, v142
	v_exp_f32_e32 v143, v143
	v_exp_f32_e32 v144, v144
	v_exp_f32_e32 v145, v145
	v_mov_b32_e32 v194, v234
	v_add_f32_e32 v236, v130, v131
	v_add_f32_e32 v236, v236, v132
	v_add_f32_e32 v236, v236, v133
	v_add_f32_e32 v236, v236, v134
	v_add_f32_e32 v236, v236, v135
	v_add_f32_e32 v236, v236, v136
	v_add_f32_e32 v236, v236, v137
	v_add_f32_e32 v236, v236, v138
	v_add_f32_e32 v236, v236, v139
	v_add_f32_e32 v236, v236, v140
	v_add_f32_e32 v236, v236, v141
	v_add_f32_e32 v236, v236, v142
	v_add_f32_e32 v236, v236, v143
	v_add_f32_e32 v236, v236, v144
	v_add_f32_e32 v236, v236, v145
	v_fma_f32 v195, v195, v233, v236
	v_mul_f32_e32 v146, v233, v146
	v_mul_f32_e32 v147, v233, v147
	v_mul_f32_e32 v148, v233, v148
	v_mul_f32_e32 v149, v233, v149
	v_mul_f32_e32 v150, v233, v150
	v_mul_f32_e32 v151, v233, v151
	v_mul_f32_e32 v152, v233, v152
	v_mul_f32_e32 v153, v233, v153
	v_mul_f32_e32 v154, v233, v154
	v_mul_f32_e32 v155, v233, v155
	v_mul_f32_e32 v156, v233, v156
	v_mul_f32_e32 v157, v233, v157
	v_mul_f32_e32 v158, v233, v158
	v_mul_f32_e32 v159, v233, v159
	v_mul_f32_e32 v160, v233, v160
	v_mul_f32_e32 v161, v233, v161
	v_mul_f32_e32 v162, v233, v162
	v_mul_f32_e32 v163, v233, v163
	v_mul_f32_e32 v164, v233, v164
	v_mul_f32_e32 v165, v233, v165
	v_mul_f32_e32 v166, v233, v166
	v_mul_f32_e32 v167, v233, v167
	v_mul_f32_e32 v168, v233, v168
	v_mul_f32_e32 v169, v233, v169
	v_mul_f32_e32 v170, v233, v170
	v_mul_f32_e32 v171, v233, v171
	v_mul_f32_e32 v172, v233, v172
	v_mul_f32_e32 v173, v233, v173
	v_mul_f32_e32 v174, v233, v174
	v_mul_f32_e32 v175, v233, v175
	v_mul_f32_e32 v176, v233, v176
	v_mul_f32_e32 v177, v233, v177
	v_cvt_pk_bf16_f32 v130, v130, v131
	v_cvt_pk_bf16_f32 v131, v132, v133
	v_cvt_pk_bf16_f32 v132, v134, v135
	v_cvt_pk_bf16_f32 v133, v136, v137
	v_cvt_pk_bf16_f32 v134, v138, v139
	v_cvt_pk_bf16_f32 v135, v140, v141
	v_cvt_pk_bf16_f32 v136, v142, v143
	v_cvt_pk_bf16_f32 v137, v144, v145
	s_waitcnt lgkmcnt(0)
	s_nop 1
	v_mfma_f32_32x32x16_bf16 v[146:161], v[178:181], v[130:133], v[146:161]
	v_mfma_f32_32x32x16_bf16 v[162:177], v[182:185], v[130:133], v[162:177]
	v_mfma_f32_32x32x16_bf16 v[146:161], v[186:189], v[134:137], v[146:161]
	v_mfma_f32_32x32x16_bf16 v[162:177], v[190:193], v[134:137], v[162:177]
	s_branch .Lattn_end3
; DI void phase_attn_a(int wv_, int vb_, int nvb_, char* ws_, const Ctx& p, char* smem) {
;     ...
;       for (int kb = 0; kb < 5; ++kb) {
;         const int kk = 32 * wave + 32 * kb + c; const int ksub0 = nb * 128 - 128 + kk;
;         bf16x8 kf[4];
;         if (ksub0 >= 0) {
;           const u16* kp = P + ((size_t)b * SEQ + (size_t)ksub0 * dil + r) * 4608 + 1536 + g * 512 + head * 64;
; #pragma unroll
;           for (int ks = 0; ks < 4; ++ks) kf[ks] = *(const bf16x8*)(kp + ks * 16 + h * 8);
;         } else {
; #pragma unroll
;           for (int ks = 0; ks < 4; ++ks) kf[ks] = zero8();
;         }
;         f32x16 sa = zero16();
; #pragma unroll
;         for (int ks = 0; ks < 4; ++ks) sa = MFMA32(kf[ks], qf[ks], sa);
;         float bm = -INFINITY;
;         const int sbase = c + 128 - 32 * kb - 4 * h;
;         const unsigned slim = (unsigned)((nb * 128 + 32 * wave + c) < 128 ? (nb * 128 + 32 * wave + c) : 128);
;         if (nb > 0 && kb >= 1 && kb <= 3) {
; #pragma unroll
;           for (int i = 0; i < 16; ++i) {
;             const int step = sbase - ((i & 3) + 8 * (i >> 2));
;             const float v = sa[i] + sBias[step];
;             sa[i] = v; bm = fmaxf(bm, v);
;           }
;         } else {
; #pragma unroll
;           for (int i = 0; i < 16; ++i) {
;             const int step = sbase - ((i & 3) + 8 * (i >> 2));
;             const bool valid = (unsigned)step <= slim;
;             const float bv = sBias[step];
;             float v = valid ? sa[i] + bv : -INFINITY;
;             sa[i] = v; bm = fmaxf(bm, v);
;           }
;         }
;         bm = fmaxf(bm, shx(bm, 32));
;         const float mnew = fmaxf(mx, bm);
;         const float mref = (mnew == -INFINITY) ? 0.f : mnew;
;         const float scale = __builtin_amdgcn_exp2f(mx - mref);
;         float ps = 0.f;
; #pragma unroll
;         for (int i = 0; i < 16; ++i) { float pv = __builtin_amdgcn_exp2f(sa[i] - mref); sa[i] = pv; ps += pv; }
;         sum = sum * scale + ps; mx = mnew;
; #pragma unroll
;         for (int i = 0; i < 16; ++i) { oacc[0][i] *= scale; oacc[1][i] *= scale; }
; #pragma unroll
;         for (int s = 0; s < 2; ++s) {
;           bf16x8 pb = pack8(sa, s);
;           const int keybase = 32 * wave + 32 * kb + 16 * s;
; #pragma unroll
;           for (int mb = 0; mb < 2; ++mb) {
;             const u16* vr = Vt + (mb * 32 + c) * 260 + keybase + 4 * h;
.Lattn_skip3:
	v_add_u32_e32 v246, 0xffffffe0, v231
	v_max_i32_e32 v246, 0, v246
	v_lshlrev_b32_e32 v246, s10, v246
	v_add_u32_e32 v246, s11, v246
	v_lshl_add_u32 v246, v246, 7, v201
	global_load_dwordx4 v[50:53], v246, s[72:73]
	global_load_dwordx4 v[54:57], v246, s[72:73] offset:32
	global_load_dwordx4 v[58:61], v246, s[72:73] offset:64
	global_load_dwordx4 v[62:65], v246, s[72:73] offset:96
.Lattn_end3:
	s_bitcmp1_b32 s2, 4
	s_cbranch_scc1 .Lattn_skip4
	v_mfma_f32_32x32x16_bf16 v[130:145], v[66:69], v[82:85], 0
	v_mfma_f32_32x32x16_bf16 v[130:145], v[70:73], v[86:89], v[130:145]
	v_mfma_f32_32x32x16_bf16 v[130:145], v[74:77], v[90:93], v[130:145]
	v_mfma_f32_32x32x16_bf16 v[130:145], v[78:81], v[94:97], v[130:145]
	v_mov_b32_e32 v246, v231
	v_max_i32_e32 v246, 0, v246
	v_lshlrev_b32_e32 v246, s10, v246
	v_add_u32_e32 v246, s11, v246
	v_lshl_add_u32 v246, v246, 7, v201
	global_load_dwordx4 v[66:69], v246, s[72:73]
	global_load_dwordx4 v[70:73], v246, s[72:73] offset:32
	global_load_dwordx4 v[74:77], v246, s[72:73] offset:64
	global_load_dwordx4 v[78:81], v246, s[72:73] offset:96
	global_load_dwordx4 v[82:85], v232, s[8:9]
	global_load_dwordx4 v[86:89], v232, s[8:9] offset:32
	global_load_dwordx4 v[90:93], v232, s[8:9] offset:64
	global_load_dwordx4 v[94:97], v232, s[8:9] offset:96
	ds_read2_b32 v[178:179], v222 offset0:31 offset1:30
	ds_read2_b32 v[180:181], v222 offset0:29 offset1:28
	ds_read2_b32 v[182:183], v222 offset0:23 offset1:22
	ds_read2_b32 v[184:185], v222 offset0:21 offset1:20
	ds_read2_b32 v[186:187], v222 offset0:15 offset1:14
	ds_read2_b32 v[188:189], v222 offset0:13 offset1:12
	ds_read2_b32 v[190:191], v222 offset0:7 offset1:6
	ds_read2_b32 v[192:193], v222 offset0:5 offset1:4
	s_waitcnt lgkmcnt(0)
	v_add_f32_e32 v130, v130, v178
	v_add_f32_e32 v131, v131, v179
	v_add_f32_e32 v132, v132, v180
	v_add_f32_e32 v133, v133, v181
	v_add_f32_e32 v134, v134, v182
	v_add_f32_e32 v135, v135, v183
	v_add_f32_e32 v136, v136, v184
	v_add_f32_e32 v137, v137, v185
	v_add_f32_e32 v138, v138, v186
	v_add_f32_e32 v139, v139, v187
	v_add_f32_e32 v140, v140, v188
	v_add_f32_e32 v141, v141, v189
	v_add_f32_e32 v142, v142, v190
	v_add_f32_e32 v143, v143, v191
	v_add_f32_e32 v144, v144, v192
	v_add_f32_e32 v145, v145, v193
	ds_read_b64 v[178:179], v221 offset:256
	ds_read_b64 v[180:181], v221 offset:272
	ds_read_b64 v[182:183], v221 offset:16896
	ds_read_b64 v[184:185], v221 offset:16912
	ds_read_b64 v[186:187], v221 offset:288
	ds_read_b64 v[188:189], v221 offset:304
	ds_read_b64 v[190:191], v221 offset:16928
	ds_read_b64 v[192:193], v221 offset:16944
	v_max3_f32 v235, v130, v131, v132
	v_max3_f32 v235, v235, v133, v134
	v_max3_f32 v235, v235, v135, v136
	v_max3_f32 v235, v235, v137, v138
	v_max3_f32 v235, v235, v139, v140
	v_max3_f32 v235, v235, v141, v142
	v_max3_f32 v235, v235, v143, v144
	v_max_f32_e32 v235, v235, v145
	v_mov_b32_e32 v196, v235
	s_nop 1
	v_permlane32_swap_b32_e32 v196, v235
	v_max_f32_e32 v235, v235, v196
	v_max_f32_e32 v234, v194, v235
	v_cmp_eq_f32_e32 vcc, 0xff800000, v234
	s_nop 1
	v_cndmask_b32_e64 v237, v234, 0, vcc
	v_sub_f32_e32 v196, v194, v237
	v_exp_f32_e32 v233, v196
	v_sub_f32_e32 v130, v130, v237
	v_sub_f32_e32 v131, v131, v237
	v_sub_f32_e32 v132, v132, v237
	v_sub_f32_e32 v133, v133, v237
	v_sub_f32_e32 v134, v134, v237
	v_sub_f32_e32 v135, v135, v237
	v_sub_f32_e32 v136, v136, v237
	v_sub_f32_e32 v137, v137, v237
	v_sub_f32_e32 v138, v138, v237
	v_sub_f32_e32 v139, v139, v237
	v_sub_f32_e32 v140, v140, v237
	v_sub_f32_e32 v141, v141, v237
	v_sub_f32_e32 v142, v142, v237
	v_sub_f32_e32 v143, v143, v237
	v_sub_f32_e32 v144, v144, v237
	v_sub_f32_e32 v145, v145, v237
	v_exp_f32_e32 v130, v130
	v_exp_f32_e32 v131, v131
	v_exp_f32_e32 v132, v132
	v_exp_f32_e32 v133, v133
	v_exp_f32_e32 v134, v134
	v_exp_f32_e32 v135, v135
	v_exp_f32_e32 v136, v136
	v_exp_f32_e32 v137, v137
	v_exp_f32_e32 v138, v138
	v_exp_f32_e32 v139, v139
	v_exp_f32_e32 v140, v140
	v_exp_f32_e32 v141, v141
	v_exp_f32_e32 v142, v142
	v_exp_f32_e32 v143, v143
	v_exp_f32_e32 v144, v144
	v_exp_f32_e32 v145, v145
	v_mov_b32_e32 v194, v234
	v_add_f32_e32 v236, v130, v131
	v_add_f32_e32 v236, v236, v132
	v_add_f32_e32 v236, v236, v133
	v_add_f32_e32 v236, v236, v134
	v_add_f32_e32 v236, v236, v135
	v_add_f32_e32 v236, v236, v136
	v_add_f32_e32 v236, v236, v137
	v_add_f32_e32 v236, v236, v138
	v_add_f32_e32 v236, v236, v139
	v_add_f32_e32 v236, v236, v140
	v_add_f32_e32 v236, v236, v141
	v_add_f32_e32 v236, v236, v142
	v_add_f32_e32 v236, v236, v143
	v_add_f32_e32 v236, v236, v144
	v_add_f32_e32 v236, v236, v145
	v_fma_f32 v195, v195, v233, v236
	v_mul_f32_e32 v146, v233, v146
	v_mul_f32_e32 v147, v233, v147
	v_mul_f32_e32 v148, v233, v148
	v_mul_f32_e32 v149, v233, v149
	v_mul_f32_e32 v150, v233, v150
	v_mul_f32_e32 v151, v233, v151
	v_mul_f32_e32 v152, v233, v152
	v_mul_f32_e32 v153, v233, v153
	v_mul_f32_e32 v154, v233, v154
	v_mul_f32_e32 v155, v233, v155
	v_mul_f32_e32 v156, v233, v156
	v_mul_f32_e32 v157, v233, v157
	v_mul_f32_e32 v158, v233, v158
	v_mul_f32_e32 v159, v233, v159
	v_mul_f32_e32 v160, v233, v160
	v_mul_f32_e32 v161, v233, v161
	v_mul_f32_e32 v162, v233, v162
	v_mul_f32_e32 v163, v233, v163
	v_mul_f32_e32 v164, v233, v164
	v_mul_f32_e32 v165, v233, v165
	v_mul_f32_e32 v166, v233, v166
	v_mul_f32_e32 v167, v233, v167
	v_mul_f32_e32 v168, v233, v168
	v_mul_f32_e32 v169, v233, v169
	v_mul_f32_e32 v170, v233, v170
	v_mul_f32_e32 v171, v233, v171
	v_mul_f32_e32 v172, v233, v172
	v_mul_f32_e32 v173, v233, v173
	v_mul_f32_e32 v174, v233, v174
	v_mul_f32_e32 v175, v233, v175
	v_mul_f32_e32 v176, v233, v176
	v_mul_f32_e32 v177, v233, v177
	v_cvt_pk_bf16_f32 v130, v130, v131
	v_cvt_pk_bf16_f32 v131, v132, v133
	v_cvt_pk_bf16_f32 v132, v134, v135
	v_cvt_pk_bf16_f32 v133, v136, v137
	v_cvt_pk_bf16_f32 v134, v138, v139
	v_cvt_pk_bf16_f32 v135, v140, v141
	v_cvt_pk_bf16_f32 v136, v142, v143
	v_cvt_pk_bf16_f32 v137, v144, v145
	s_waitcnt lgkmcnt(0)
	s_nop 1
	v_mfma_f32_32x32x16_bf16 v[146:161], v[178:181], v[130:133], v[146:161]
	v_mfma_f32_32x32x16_bf16 v[162:177], v[182:185], v[130:133], v[162:177]
	v_mfma_f32_32x32x16_bf16 v[146:161], v[186:189], v[134:137], v[146:161]
	v_mfma_f32_32x32x16_bf16 v[162:177], v[190:193], v[134:137], v[162:177]
	s_branch .Lattn_end4
.Lattn_skip4:
	v_mov_b32_e32 v246, v231
	v_max_i32_e32 v246, 0, v246
	v_lshlrev_b32_e32 v246, s10, v246
	v_add_u32_e32 v246, s11, v246
	v_lshl_add_u32 v246, v246, 7, v201
	global_load_dwordx4 v[66:69], v246, s[72:73]
	global_load_dwordx4 v[70:73], v246, s[72:73] offset:32
	global_load_dwordx4 v[74:77], v246, s[72:73] offset:64
	global_load_dwordx4 v[78:81], v246, s[72:73] offset:96
	global_load_dwordx4 v[82:85], v232, s[8:9]
	global_load_dwordx4 v[86:89], v232, s[8:9] offset:32
	global_load_dwordx4 v[90:93], v232, s[8:9] offset:64
	global_load_dwordx4 v[94:97], v232, s[8:9] offset:96

; __device__ __forceinline__ unsigned cvt_pk_bf16(float lo, float hi) { unsigned r; asm volatile("v_cvt_pk_bf16_f32 %0, %1, %2" : "=v"(r) : "v"(lo), "v"(hi)); return r; }
;     __device__ __forceinline__ void operator()(const f32x4 (&acc)[2][2][4][2], const Unit& u, int wr, int wc, int fr, int fq) const {
;     ...
; #pragma unroll
;         for (int ai = 0; ai < 2; ++ai)
; #pragma unroll
;             for (int m = 0; m < 4; ++m) { bf16_t* rowp = O + (size_t)(row0 + ai * HALF + m * 16) * ldc + col0;
; #pragma unroll
;                 for (int bj = 0; bj < 2; ++bj) { f32x4 v0 = acc[ai][bj][m][0], v1 = acc[ai][bj][m][1];
;                     const float r = hn ? rsqrtf(part[ai][m][bj] * (1.0f / 64.0f) + 1e-6f) : 1.0f;
; #pragma unroll
;                     for (int j = 0; j < 4; ++j) { v0[j] *= r * g8[j]; v1[j] *= r * g8[4 + j]; }
;                     u32x4 w; w.x = cvt_pk_bf16(v0[0], v0[1]); w.y = cvt_pk_bf16(v0[2], v0[3]); w.z = cvt_pk_bf16(v1[0], v1[1]); w.w = cvt_pk_bf16(v1[2], v1[3]);
;                     *(u32x4*)(rowp + bj * HALF) = w; } }
.LBB0_734:
	v_mul_f32_e32 v177, 0x4b800000, v161
	v_cmp_gt_f32_e32 vcc, s51, v161
	v_lshl_or_b32 v152, s68, 8, v170
	v_lshl_add_u32 v176, s72, 8, v166
	v_cndmask_b32_e32 v161, v161, v177, vcc
	v_rsq_f32_e32 v161, v161
	v_ashrrev_i32_e32 v153, 31, v152
	v_mov_b64_e32 v[150:151], s[86:87]
	v_mad_i64_i32 v[178:179], s[0:1], v176, s37, v[150:151]
	v_mul_f32_e32 v177, 0x45800000, v161
	v_cndmask_b32_e32 v161, v161, v177, vcc
	v_cndmask_b32_e64 v161, 1.0, v161, s[6:7]
	v_mul_f32_e32 v177, v161, v163
	v_mul_f32_e32 v126, v126, v177
	v_mul_f32_e32 v177, v161, v173
	v_mul_f32_e32 v177, v122, v177
	v_mul_f32_e32 v122, v161, v162
	v_mul_f32_e32 v122, v127, v122
	v_mul_f32_e32 v127, v161, v172
	v_mul_f32_e32 v127, v123, v127
	v_mul_f32_e32 v123, v161, v165
	v_mul_f32_e32 v123, v128, v123
	v_mul_f32_e32 v128, v161, v175
	v_mul_f32_e32 v128, v124, v128
	v_mul_f32_e32 v124, v161, v164
	v_mul_f32_e32 v124, v129, v124
	v_cvt_pk_bf16_f32 v122, v126, v122
	v_cvt_pk_bf16_f32 v123, v123, v124
	v_mul_f32_e32 v124, 0x4b800000, v160
	v_cmp_gt_f32_e32 vcc, s51, v160
	v_lshrrev_b32_e32 v153, 6, v152
	v_and_b32_e32 v152, 63, v152
	v_lshlrev_b32_e32 v152, 1, v152
	v_lshl_or_b32 v152, v153, 22, v152
	v_mov_b32_e32 v153, 0
	s_mov_b64 s[100:101], 0x800000
	v_mul_f32_e32 v129, v161, v174
	v_cndmask_b32_e32 v124, v160, v124, vcc
	v_rsq_f32_e32 v126, v124
	v_lshl_add_u64 v[178:179], v[178:179], 0, v[152:153]
	v_mul_f32_e32 v125, v125, v129
	v_cvt_pk_bf16_f32 v124, v177, v127
	v_cvt_pk_bf16_f32 v125, v128, v125
	global_store_dwordx4 v[178:179], v[122:125], off
	s_mov_b32 s68, s10
	s_mov_b32 s72, s12
	v_mul_f32_e32 v122, 0x45800000, v126
	v_cndmask_b32_e32 v122, v126, v122, vcc
	v_cndmask_b32_e64 v122, 1.0, v122, s[6:7]
	v_mul_f32_e32 v123, v122, v163
	v_mul_f32_e32 v118, v118, v123
	v_mul_f32_e32 v123, v122, v173
	v_mul_f32_e32 v123, v114, v123
	v_mul_f32_e32 v114, v122, v162
	v_mul_f32_e32 v114, v119, v114
	v_mul_f32_e32 v119, v122, v172
	v_mul_f32_e32 v119, v115, v119
	v_mul_f32_e32 v115, v122, v165
	v_mul_f32_e32 v115, v120, v115
	v_mul_f32_e32 v120, v122, v175
	v_mul_f32_e32 v120, v116, v120
	v_mul_f32_e32 v116, v122, v164
	v_mul_f32_e32 v116, v121, v116
	v_mul_f32_e32 v121, v122, v174
	v_mul_f32_e32 v117, v117, v121
	v_cvt_pk_bf16_f32 v114, v118, v114
	v_cvt_pk_bf16_f32 v115, v115, v116
	v_cvt_pk_bf16_f32 v116, v123, v119
	v_cvt_pk_bf16_f32 v117, v120, v117
	v_lshl_add_u64 v[178:179], v[178:179], 0, s[100:101]
	global_store_dwordx4 v[178:179], v[114:117], off
	v_cmp_gt_f32_e32 vcc, s51, v159
	s_mov_b64 s[8:9], s[18:19]
	v_mul_f32_e32 v115, 0x4b800000, v159
	v_cndmask_b32_e32 v115, v159, v115, vcc
	v_rsq_f32_e32 v116, v115
	v_or_b32_e32 v114, 16, v176
	v_mad_i64_i32 v[114:115], s[0:1], v114, s37, v[150:151]
	v_mul_f32_e32 v117, 0x45800000, v116
	v_cndmask_b32_e32 v116, v116, v117, vcc
	v_cndmask_b32_e64 v116, 1.0, v116, s[6:7]
	v_mul_f32_e32 v117, v116, v163
	v_mul_f32_e32 v110, v110, v117
	v_mul_f32_e32 v117, v116, v173
	v_mul_f32_e32 v117, v106, v117
	v_mul_f32_e32 v106, v116, v162
	v_mul_f32_e32 v106, v111, v106
	v_mul_f32_e32 v111, v116, v172
	v_mul_f32_e32 v111, v107, v111
	v_mul_f32_e32 v107, v116, v165
	v_mul_f32_e32 v107, v112, v107
	v_mul_f32_e32 v112, v116, v175
	v_mul_f32_e32 v112, v108, v112
	v_mul_f32_e32 v108, v116, v164
	v_mul_f32_e32 v108, v113, v108
	v_cvt_pk_bf16_f32 v106, v110, v106
	v_cvt_pk_bf16_f32 v107, v107, v108
	v_mul_f32_e32 v108, 0x4b800000, v158
	v_cmp_gt_f32_e32 vcc, s51, v158
	v_mul_f32_e32 v113, v116, v174
	v_lshl_add_u64 v[114:115], v[114:115], 0, v[152:153]
	v_cndmask_b32_e32 v108, v158, v108, vcc
	v_rsq_f32_e32 v110, v108
	v_mul_f32_e32 v109, v109, v113
	v_cvt_pk_bf16_f32 v108, v117, v111
	v_cvt_pk_bf16_f32 v109, v112, v109
	global_store_dwordx4 v[114:115], v[106:109], off
	s_nop 1
	v_mul_f32_e32 v106, 0x45800000, v110
	v_cndmask_b32_e32 v106, v110, v106, vcc
	v_cndmask_b32_e64 v106, 1.0, v106, s[6:7]
	v_mul_f32_e32 v107, v106, v163
	v_mul_f32_e32 v102, v102, v107
	v_mul_f32_e32 v107, v106, v173
	v_mul_f32_e32 v107, v98, v107
	v_mul_f32_e32 v98, v106, v162
	v_mul_f32_e32 v98, v103, v98
	v_mul_f32_e32 v103, v106, v172
	v_mul_f32_e32 v103, v99, v103
	v_mul_f32_e32 v99, v106, v165
	v_mul_f32_e32 v99, v104, v99
	v_mul_f32_e32 v104, v106, v175
	v_mul_f32_e32 v104, v100, v104
	v_mul_f32_e32 v100, v106, v164
	v_mul_f32_e32 v100, v105, v100
	v_mul_f32_e32 v105, v106, v174
	v_mul_f32_e32 v101, v101, v105
	v_cvt_pk_bf16_f32 v98, v102, v98
	v_cvt_pk_bf16_f32 v99, v99, v100
	v_cvt_pk_bf16_f32 v100, v107, v103
	v_cvt_pk_bf16_f32 v101, v104, v101
	v_lshl_add_u64 v[114:115], v[114:115], 0, s[100:101]
	global_store_dwordx4 v[114:115], v[98:101], off
	v_cmp_gt_f32_e32 vcc, s51, v157
	s_nop 0
	v_mul_f32_e32 v99, 0x4b800000, v157
	v_cndmask_b32_e32 v99, v157, v99, vcc
	v_rsq_f32_e32 v100, v99
	v_or_b32_e32 v98, 32, v176
	v_mad_i64_i32 v[98:99], s[0:1], v98, s37, v[150:151]
	v_mul_f32_e32 v101, 0x45800000, v100
	v_cndmask_b32_e32 v100, v100, v101, vcc
	v_cndmask_b32_e64 v100, 1.0, v100, s[6:7]
	v_mul_f32_e32 v101, v100, v163
	v_mul_f32_e32 v94, v94, v101
	v_mul_f32_e32 v101, v100, v173
	v_mul_f32_e32 v101, v90, v101
	v_mul_f32_e32 v90, v100, v162
	v_mul_f32_e32 v90, v95, v90
	v_mul_f32_e32 v95, v100, v172
	v_mul_f32_e32 v95, v91, v95
	v_mul_f32_e32 v91, v100, v165
	v_mul_f32_e32 v91, v96, v91
	v_mul_f32_e32 v96, v100, v175
	v_mul_f32_e32 v96, v92, v96
	v_mul_f32_e32 v92, v100, v164
	v_mul_f32_e32 v92, v97, v92
	v_cvt_pk_bf16_f32 v90, v94, v90
	v_cvt_pk_bf16_f32 v91, v91, v92
	v_mul_f32_e32 v92, 0x4b800000, v156
	v_cmp_gt_f32_e32 vcc, s51, v156
	v_mul_f32_e32 v97, v100, v174
	v_lshl_add_u64 v[98:99], v[98:99], 0, v[152:153]
	v_cndmask_b32_e32 v92, v156, v92, vcc
; __device__ __forceinline__ unsigned cvt_pk_bf16(float lo, float hi) { unsigned r; asm volatile("v_cvt_pk_bf16_f32 %0, %1, %2" : "=v"(r) : "v"(lo), "v"(hi)); return r; }
;     __device__ __forceinline__ void operator()(const f32x4 (&acc)[2][2][4][2], const Unit& u, int wr, int wc, int fr, int fq) const {
;     ...
; #pragma unroll
;         for (int ai = 0; ai < 2; ++ai)
; #pragma unroll
;             for (int m = 0; m < 4; ++m) { bf16_t* rowp = O + (size_t)(row0 + ai * HALF + m * 16) * ldc + col0;
; #pragma unroll
;                 for (int bj = 0; bj < 2; ++bj) { f32x4 v0 = acc[ai][bj][m][0], v1 = acc[ai][bj][m][1];
;                     const float r = hn ? rsqrtf(part[ai][m][bj] * (1.0f / 64.0f) + 1e-6f) : 1.0f;
; #pragma unroll
;                     for (int j = 0; j < 4; ++j) { v0[j] *= r * g8[j]; v1[j] *= r * g8[4 + j]; }
;                     u32x4 w; w.x = cvt_pk_bf16(v0[0], v0[1]); w.y = cvt_pk_bf16(v0[2], v0[3]); w.z = cvt_pk_bf16(v1[0], v1[1]); w.w = cvt_pk_bf16(v1[2], v1[3]);
;                     *(u32x4*)(rowp + bj * HALF) = w; } }
	v_rsq_f32_e32 v94, v92
	v_mul_f32_e32 v93, v93, v97
	v_cvt_pk_bf16_f32 v92, v101, v95
	v_cvt_pk_bf16_f32 v93, v96, v93
	global_store_dwordx4 v[98:99], v[90:93], off
	s_nop 1
	v_mul_f32_e32 v90, 0x45800000, v94
	v_cndmask_b32_e32 v90, v94, v90, vcc
	v_cndmask_b32_e64 v90, 1.0, v90, s[6:7]
	v_mul_f32_e32 v91, v90, v163
	v_mul_f32_e32 v86, v86, v91
	v_mul_f32_e32 v91, v90, v173
	v_mul_f32_e32 v91, v82, v91
	v_mul_f32_e32 v82, v90, v162
	v_mul_f32_e32 v82, v87, v82
	v_mul_f32_e32 v87, v90, v172
	v_mul_f32_e32 v87, v83, v87
	v_mul_f32_e32 v83, v90, v165
	v_mul_f32_e32 v83, v88, v83
	v_mul_f32_e32 v88, v90, v175
	v_mul_f32_e32 v88, v84, v88
	v_mul_f32_e32 v84, v90, v164
	v_mul_f32_e32 v84, v89, v84
	v_mul_f32_e32 v89, v90, v174
	v_mul_f32_e32 v85, v85, v89
	v_cvt_pk_bf16_f32 v82, v86, v82
	v_cvt_pk_bf16_f32 v83, v83, v84
	v_cvt_pk_bf16_f32 v84, v91, v87
	v_cvt_pk_bf16_f32 v85, v88, v85
	v_lshl_add_u64 v[98:99], v[98:99], 0, s[100:101]
	global_store_dwordx4 v[98:99], v[82:85], off
	v_cmp_gt_f32_e32 vcc, s51, v155
	s_nop 0
	v_mul_f32_e32 v83, 0x4b800000, v155
	v_cndmask_b32_e32 v83, v155, v83, vcc
	v_rsq_f32_e32 v84, v83
	v_or_b32_e32 v82, 48, v176
	v_mad_i64_i32 v[82:83], s[0:1], v82, s37, v[150:151]
	v_mul_f32_e32 v85, 0x45800000, v84
	v_cndmask_b32_e32 v84, v84, v85, vcc
	v_cndmask_b32_e64 v84, 1.0, v84, s[6:7]
	v_mul_f32_e32 v85, v84, v163
	v_mul_f32_e32 v78, v78, v85
	v_mul_f32_e32 v85, v84, v173
	v_mul_f32_e32 v85, v74, v85
	v_mul_f32_e32 v74, v84, v162
	v_mul_f32_e32 v74, v79, v74
	v_mul_f32_e32 v79, v84, v172
	v_mul_f32_e32 v79, v75, v79
	v_mul_f32_e32 v75, v84, v165
	v_mul_f32_e32 v75, v80, v75
	v_mul_f32_e32 v80, v84, v175
	v_mul_f32_e32 v80, v76, v80
	v_mul_f32_e32 v76, v84, v164
	v_mul_f32_e32 v76, v81, v76
	v_cvt_pk_bf16_f32 v74, v78, v74
	v_cvt_pk_bf16_f32 v75, v75, v76
	v_mul_f32_e32 v76, 0x4b800000, v154
	v_cmp_gt_f32_e32 vcc, s51, v154
	v_mul_f32_e32 v81, v84, v174
	v_lshl_add_u64 v[82:83], v[82:83], 0, v[152:153]
	v_cndmask_b32_e32 v76, v154, v76, vcc
	v_rsq_f32_e32 v78, v76
	v_mul_f32_e32 v77, v77, v81
	v_cvt_pk_bf16_f32 v76, v85, v79
	v_cvt_pk_bf16_f32 v77, v80, v77
	global_store_dwordx4 v[82:83], v[74:77], off
	s_nop 1
	v_mul_f32_e32 v74, 0x45800000, v78
	v_cndmask_b32_e32 v74, v78, v74, vcc
	v_cndmask_b32_e64 v74, 1.0, v74, s[6:7]
	v_mul_f32_e32 v75, v74, v163
	v_mul_f32_e32 v70, v70, v75
	v_mul_f32_e32 v75, v74, v173
	v_mul_f32_e32 v75, v66, v75
	v_mul_f32_e32 v66, v74, v162
	v_mul_f32_e32 v66, v71, v66
	v_mul_f32_e32 v71, v74, v172
	v_mul_f32_e32 v71, v67, v71
	v_mul_f32_e32 v67, v74, v165
	v_mul_f32_e32 v67, v72, v67
	v_mul_f32_e32 v72, v74, v175
	v_mul_f32_e32 v72, v68, v72
	v_mul_f32_e32 v68, v74, v164
	v_mul_f32_e32 v68, v73, v68
	v_mul_f32_e32 v73, v74, v174
	v_mul_f32_e32 v69, v69, v73
	v_cvt_pk_bf16_f32 v66, v70, v66
	v_cvt_pk_bf16_f32 v67, v67, v68
	v_cvt_pk_bf16_f32 v68, v75, v71
	v_cvt_pk_bf16_f32 v69, v72, v69
	v_lshl_add_u64 v[82:83], v[82:83], 0, s[100:101]
	global_store_dwordx4 v[82:83], v[66:69], off
	v_cmp_gt_f32_e32 vcc, s51, v149
	s_nop 0
	v_mul_f32_e32 v67, 0x4b800000, v149
	v_cndmask_b32_e32 v67, v149, v67, vcc
	v_rsq_f32_e32 v68, v67
	v_add_u32_e32 v66, 0x80, v176
	v_mad_i64_i32 v[66:67], s[0:1], v66, s37, v[150:151]
	v_mul_f32_e32 v69, 0x45800000, v68
	v_cndmask_b32_e32 v68, v68, v69, vcc
	v_cndmask_b32_e64 v68, 1.0, v68, s[6:7]
	v_mul_f32_e32 v69, v68, v163
	v_mul_f32_e32 v62, v62, v69
	v_mul_f32_e32 v69, v68, v173
	v_mul_f32_e32 v69, v58, v69
	v_mul_f32_e32 v58, v68, v162
	v_mul_f32_e32 v58, v63, v58
	v_mul_f32_e32 v63, v68, v172
	v_mul_f32_e32 v63, v59, v63
	v_mul_f32_e32 v59, v68, v165
	v_mul_f32_e32 v59, v64, v59
	v_mul_f32_e32 v64, v68, v175
	v_mul_f32_e32 v64, v60, v64
	v_mul_f32_e32 v60, v68, v164
	v_mul_f32_e32 v60, v65, v60
	v_cvt_pk_bf16_f32 v58, v62, v58
	v_cvt_pk_bf16_f32 v59, v59, v60
	v_mul_f32_e32 v60, 0x4b800000, v148
	v_cmp_gt_f32_e32 vcc, s51, v148
	v_mul_f32_e32 v65, v68, v174
	v_lshl_add_u64 v[66:67], v[66:67], 0, v[152:153]
	v_cndmask_b32_e32 v60, v148, v60, vcc
	v_rsq_f32_e32 v62, v60
	v_mul_f32_e32 v61, v61, v65
	v_cvt_pk_bf16_f32 v60, v69, v63
	v_cvt_pk_bf16_f32 v61, v64, v61
	global_store_dwordx4 v[66:67], v[58:61], off
	s_nop 1
	v_mul_f32_e32 v58, 0x45800000, v62
	v_cndmask_b32_e32 v58, v62, v58, vcc
	v_cndmask_b32_e64 v58, 1.0, v58, s[6:7]
	v_mul_f32_e32 v59, v58, v163
	v_mul_f32_e32 v54, v54, v59
	v_mul_f32_e32 v59, v58, v173
	v_mul_f32_e32 v59, v50, v59
	v_mul_f32_e32 v50, v58, v162
	v_mul_f32_e32 v50, v55, v50
	v_mul_f32_e32 v55, v58, v172
	v_mul_f32_e32 v55, v51, v55
	v_mul_f32_e32 v51, v58, v165
	v_mul_f32_e32 v51, v56, v51
	v_mul_f32_e32 v56, v58, v175
	v_mul_f32_e32 v56, v52, v56
	v_mul_f32_e32 v52, v58, v164
	v_mul_f32_e32 v52, v57, v52
	v_mul_f32_e32 v57, v58, v174
	v_mul_f32_e32 v53, v53, v57
	v_cvt_pk_bf16_f32 v50, v54, v50
	v_cvt_pk_bf16_f32 v51, v51, v52
	v_cvt_pk_bf16_f32 v52, v59, v55
	v_cvt_pk_bf16_f32 v53, v56, v53
	v_lshl_add_u64 v[66:67], v[66:67], 0, s[100:101]
	global_store_dwordx4 v[66:67], v[50:53], off
	v_cmp_gt_f32_e32 vcc, s51, v147
	s_nop 0
	v_mul_f32_e32 v51, 0x4b800000, v147
	v_cndmask_b32_e32 v51, v147, v51, vcc
	v_rsq_f32_e32 v52, v51
	v_add_u32_e32 v50, 0x90, v176
	v_mad_i64_i32 v[50:51], s[0:1], v50, s37, v[150:151]
	v_mul_f32_e32 v53, 0x45800000, v52
	v_cndmask_b32_e32 v52, v52, v53, vcc
	v_cndmask_b32_e64 v52, 1.0, v52, s[6:7]
	v_mul_f32_e32 v53, v52, v163
	v_mul_f32_e32 v46, v46, v53
	v_mul_f32_e32 v53, v52, v173
	v_mul_f32_e32 v53, v42, v53
	v_mul_f32_e32 v42, v52, v162
	v_mul_f32_e32 v42, v47, v42
; __device__ __forceinline__ unsigned cvt_pk_bf16(float lo, float hi) { unsigned r; asm volatile("v_cvt_pk_bf16_f32 %0, %1, %2" : "=v"(r) : "v"(lo), "v"(hi)); return r; }
;     __device__ __forceinline__ void operator()(const f32x4 (&acc)[2][2][4][2], const Unit& u, int wr, int wc, int fr, int fq) const {
;     ...
; #pragma unroll
;         for (int ai = 0; ai < 2; ++ai)
; #pragma unroll
;             for (int m = 0; m < 4; ++m) { bf16_t* rowp = O + (size_t)(row0 + ai * HALF + m * 16) * ldc + col0;
; #pragma unroll
;                 for (int bj = 0; bj < 2; ++bj) { f32x4 v0 = acc[ai][bj][m][0], v1 = acc[ai][bj][m][1];
;                     const float r = hn ? rsqrtf(part[ai][m][bj] * (1.0f / 64.0f) + 1e-6f) : 1.0f;
; #pragma unroll
;                     for (int j = 0; j < 4; ++j) { v0[j] *= r * g8[j]; v1[j] *= r * g8[4 + j]; }
;                     u32x4 w; w.x = cvt_pk_bf16(v0[0], v0[1]); w.y = cvt_pk_bf16(v0[2], v0[3]); w.z = cvt_pk_bf16(v1[0], v1[1]); w.w = cvt_pk_bf16(v1[2], v1[3]);
;                     *(u32x4*)(rowp + bj * HALF) = w; } }
	v_mul_f32_e32 v47, v52, v172
	v_mul_f32_e32 v47, v43, v47
	v_mul_f32_e32 v43, v52, v165
	v_mul_f32_e32 v43, v48, v43
	v_mul_f32_e32 v48, v52, v175
	v_mul_f32_e32 v48, v44, v48
	v_mul_f32_e32 v44, v52, v164
	v_mul_f32_e32 v44, v49, v44
	v_cvt_pk_bf16_f32 v42, v46, v42
	v_cvt_pk_bf16_f32 v43, v43, v44
	v_mul_f32_e32 v44, 0x4b800000, v146
	v_cmp_gt_f32_e32 vcc, s51, v146
	v_mul_f32_e32 v49, v52, v174
	v_lshl_add_u64 v[50:51], v[50:51], 0, v[152:153]
	v_cndmask_b32_e32 v44, v146, v44, vcc
	v_rsq_f32_e32 v46, v44
	v_mul_f32_e32 v45, v45, v49
	v_cvt_pk_bf16_f32 v44, v53, v47
	v_cvt_pk_bf16_f32 v45, v48, v45
	global_store_dwordx4 v[50:51], v[42:45], off
	s_nop 1
	v_mul_f32_e32 v42, 0x45800000, v46
	v_cndmask_b32_e32 v42, v46, v42, vcc
	v_cndmask_b32_e64 v42, 1.0, v42, s[6:7]
	v_mul_f32_e32 v43, v42, v163
	v_mul_f32_e32 v38, v38, v43
	v_mul_f32_e32 v43, v42, v173
	v_mul_f32_e32 v43, v34, v43
	v_mul_f32_e32 v34, v42, v162
	v_mul_f32_e32 v34, v39, v34
	v_mul_f32_e32 v39, v42, v172
	v_mul_f32_e32 v39, v35, v39
	v_mul_f32_e32 v35, v42, v165
	v_mul_f32_e32 v35, v40, v35
	v_mul_f32_e32 v40, v42, v175
	v_mul_f32_e32 v40, v36, v40
	v_mul_f32_e32 v36, v42, v164
	v_mul_f32_e32 v36, v41, v36
	v_mul_f32_e32 v41, v42, v174
	v_mul_f32_e32 v37, v37, v41
	v_cvt_pk_bf16_f32 v34, v38, v34
	v_cvt_pk_bf16_f32 v35, v35, v36
	v_cvt_pk_bf16_f32 v36, v43, v39
	v_cvt_pk_bf16_f32 v37, v40, v37
	v_lshl_add_u64 v[50:51], v[50:51], 0, s[100:101]
	global_store_dwordx4 v[50:51], v[34:37], off
	v_cmp_gt_f32_e32 vcc, s51, v145
	s_nop 0
	v_mul_f32_e32 v35, 0x4b800000, v145
	v_cndmask_b32_e32 v35, v145, v35, vcc
	v_rsq_f32_e32 v36, v35
	v_add_u32_e32 v34, 0xa0, v176
	v_mad_i64_i32 v[34:35], s[0:1], v34, s37, v[150:151]
	v_mul_f32_e32 v37, 0x45800000, v36
	v_cndmask_b32_e32 v36, v36, v37, vcc
	v_cndmask_b32_e64 v36, 1.0, v36, s[6:7]
	v_mul_f32_e32 v37, v36, v163
	v_mul_f32_e32 v30, v30, v37
	v_mul_f32_e32 v37, v36, v173
	v_mul_f32_e32 v37, v26, v37
	v_mul_f32_e32 v26, v36, v162
	v_mul_f32_e32 v26, v31, v26
	v_mul_f32_e32 v31, v36, v172
	v_mul_f32_e32 v31, v27, v31
	v_mul_f32_e32 v27, v36, v165
	v_mul_f32_e32 v27, v32, v27
	v_mul_f32_e32 v32, v36, v175
	v_mul_f32_e32 v32, v28, v32
	v_mul_f32_e32 v28, v36, v164
	v_mul_f32_e32 v28, v33, v28
	v_cvt_pk_bf16_f32 v26, v30, v26
	v_cvt_pk_bf16_f32 v27, v27, v28
	v_mul_f32_e32 v28, 0x4b800000, v144
	v_cmp_gt_f32_e32 vcc, s51, v144
	v_mul_f32_e32 v33, v36, v174
	v_lshl_add_u64 v[34:35], v[34:35], 0, v[152:153]
	v_cndmask_b32_e32 v28, v144, v28, vcc
	v_rsq_f32_e32 v30, v28
	v_mul_f32_e32 v29, v29, v33
	v_cvt_pk_bf16_f32 v28, v37, v31
	v_cvt_pk_bf16_f32 v29, v32, v29
	global_store_dwordx4 v[34:35], v[26:29], off
	s_nop 1
	v_mul_f32_e32 v26, 0x45800000, v30
	v_cndmask_b32_e32 v26, v30, v26, vcc
	v_cndmask_b32_e64 v26, 1.0, v26, s[6:7]
	v_mul_f32_e32 v27, v26, v163
	v_mul_f32_e32 v22, v22, v27
	v_mul_f32_e32 v27, v26, v173
	v_mul_f32_e32 v27, v18, v27
	v_mul_f32_e32 v18, v26, v162
	v_mul_f32_e32 v18, v23, v18
	v_mul_f32_e32 v23, v26, v172
	v_mul_f32_e32 v23, v19, v23
	v_mul_f32_e32 v19, v26, v165
	v_mul_f32_e32 v19, v24, v19
	v_mul_f32_e32 v24, v26, v175
	v_mul_f32_e32 v24, v20, v24
	v_mul_f32_e32 v20, v26, v164
	v_mul_f32_e32 v20, v25, v20
	v_mul_f32_e32 v25, v26, v174
	v_mul_f32_e32 v21, v21, v25
	v_cvt_pk_bf16_f32 v18, v22, v18
	v_cvt_pk_bf16_f32 v19, v19, v20
	v_cvt_pk_bf16_f32 v20, v27, v23
	v_cvt_pk_bf16_f32 v21, v24, v21
	v_lshl_add_u64 v[34:35], v[34:35], 0, s[100:101]
	global_store_dwordx4 v[34:35], v[18:21], off
	v_cmp_gt_f32_e32 vcc, s51, v143
	s_nop 0
	v_mul_f32_e32 v19, 0x4b800000, v143
	v_cndmask_b32_e32 v19, v143, v19, vcc
	v_rsq_f32_e32 v20, v19
	v_add_u32_e32 v18, 0xb0, v176
	v_mad_i64_i32 v[18:19], s[0:1], v18, s37, v[150:151]
	v_mul_f32_e32 v21, 0x45800000, v20
	v_cndmask_b32_e32 v20, v20, v21, vcc
	v_cndmask_b32_e64 v20, 1.0, v20, s[6:7]
	v_mul_f32_e32 v21, v20, v163
	v_mul_f32_e32 v14, v14, v21
	v_mul_f32_e32 v21, v20, v173
	v_mul_f32_e32 v21, v10, v21
	v_mul_f32_e32 v10, v20, v162
	v_mul_f32_e32 v10, v15, v10
	v_mul_f32_e32 v15, v20, v172
	v_mul_f32_e32 v15, v11, v15
	v_mul_f32_e32 v11, v20, v165
	v_mul_f32_e32 v11, v16, v11
	v_mul_f32_e32 v16, v20, v175
	v_mul_f32_e32 v16, v12, v16
	v_mul_f32_e32 v12, v20, v164
	v_mul_f32_e32 v12, v17, v12
	v_cvt_pk_bf16_f32 v10, v14, v10
	v_cvt_pk_bf16_f32 v11, v11, v12
	v_mul_f32_e32 v12, 0x4b800000, v142
	v_cmp_gt_f32_e32 vcc, s51, v142
	v_mul_f32_e32 v17, v20, v174
	v_lshl_add_u64 v[18:19], v[18:19], 0, v[152:153]
	v_cndmask_b32_e32 v12, v142, v12, vcc
	v_rsq_f32_e32 v14, v12
	v_mul_f32_e32 v13, v13, v17
	v_cvt_pk_bf16_f32 v12, v21, v15
	v_cvt_pk_bf16_f32 v13, v16, v13
	global_store_dwordx4 v[18:19], v[10:13], off
	s_nop 1
	v_mul_f32_e32 v10, 0x45800000, v14
	v_cndmask_b32_e32 v10, v14, v10, vcc
	v_cndmask_b32_e64 v10, 1.0, v10, s[6:7]
	v_mul_f32_e32 v11, v10, v163
	v_mul_f32_e32 v6, v6, v11
	v_mul_f32_e32 v11, v10, v173
	v_mul_f32_e32 v11, v2, v11
	v_mul_f32_e32 v2, v10, v162
	v_mul_f32_e32 v2, v7, v2
	v_mul_f32_e32 v7, v10, v172
	v_mul_f32_e32 v7, v3, v7
	v_mul_f32_e32 v3, v10, v165
	v_mul_f32_e32 v3, v8, v3
	v_mul_f32_e32 v8, v10, v175
	v_mul_f32_e32 v8, v4, v8
	v_mul_f32_e32 v4, v10, v164
	v_mul_f32_e32 v4, v9, v4
	v_mul_f32_e32 v9, v10, v174
	v_mul_f32_e32 v5, v5, v9
	s_and_b64 vcc, exec, s[4:5]
	s_mov_b64 s[6:7], s[14:15]
	v_cvt_pk_bf16_f32 v2, v6, v2
	v_cvt_pk_bf16_f32 v3, v3, v4
	v_cvt_pk_bf16_f32 v4, v11, v7
	v_cvt_pk_bf16_f32 v5, v8, v5
	v_lshl_add_u64 v[18:19], v[18:19], 0, s[100:101]
	global_store_dwordx4 v[18:19], v[2:5], off
	s_cbranch_vccnz .LBB0_759

; __global__ void __launch_bounds__(512, 2) mega(Params pp) {
;   extern __shared__ __attribute__((aligned(16))) char smem0[];
;   cg::grid_group grid = cg::this_grid();
;   const int wv8_ = __builtin_amdgcn_readfirstlane((int)threadIdx.x >> 6);
	.amdhsa_kernel _Z4mega6Params
		.amdhsa_group_segment_fixed_size 0
		.amdhsa_private_segment_fixed_size 0
		.amdhsa_kernarg_size 504
		.amdhsa_user_sgpr_count 2
		.amdhsa_user_sgpr_dispatch_ptr 0
		.amdhsa_user_sgpr_queue_ptr 0
		.amdhsa_user_sgpr_kernarg_segment_ptr 1
		.amdhsa_user_sgpr_dispatch_id 0
		.amdhsa_user_sgpr_kernarg_preload_length 0
		.amdhsa_user_sgpr_kernarg_preload_offset 0
		.amdhsa_user_sgpr_private_segment_size 0
		.amdhsa_uses_dynamic_stack 0
		.amdhsa_enable_private_segment 0
		.amdhsa_system_sgpr_workgroup_id_x 1
		.amdhsa_system_sgpr_workgroup_id_y 0
		.amdhsa_system_sgpr_workgroup_id_z 0
		.amdhsa_system_sgpr_workgroup_info 0
		.amdhsa_system_vgpr_workitem_id 2
		.amdhsa_next_free_vgpr 256
		.amdhsa_next_free_sgpr 102
		.amdhsa_accum_offset 256
		.amdhsa_reserve_vcc 1
		.amdhsa_float_round_mode_32 0
		.amdhsa_float_round_mode_16_64 0
		.amdhsa_float_denorm_mode_32 3
		.amdhsa_float_denorm_mode_16_64 3
		.amdhsa_dx10_clamp 1
		.amdhsa_ieee_mode 1
		.amdhsa_fp16_overflow 0
		.amdhsa_tg_split 0
		.amdhsa_exception_fp_ieee_invalid_op 0
		.amdhsa_exception_fp_denorm_src 0
		.amdhsa_exception_fp_ieee_div_zero 0
		.amdhsa_exception_fp_ieee_overflow 0
		.amdhsa_exception_fp_ieee_underflow 0
		.amdhsa_exception_fp_ieee_inexact 0
		.amdhsa_exception_int_div_zero 0
	.end_amdhsa_kernel

; __global__ void __launch_bounds__(512, 2) mega(Params pp) {
;   extern __shared__ __attribute__((aligned(16))) char smem0[];
;   cg::grid_group grid = cg::this_grid();
;   const int wv8_ = __builtin_amdgcn_readfirstlane((int)threadIdx.x >> 6);
amdhsa.kernels:
  - .agpr_count:     0
    .args:
      - .offset:         0
        .size:           248
        .value_kind:     by_value
      - .offset:         248
        .size:           4
        .value_kind:     hidden_block_count_x
      - .offset:         252
        .size:           4
        .value_kind:     hidden_block_count_y
      - .offset:         256
        .size:           4
        .value_kind:     hidden_block_count_z
      - .offset:         260
        .size:           2
        .value_kind:     hidden_group_size_x
      - .offset:         262
        .size:           2
        .value_kind:     hidden_group_size_y
      - .offset:         264
        .size:           2
        .value_kind:     hidden_group_size_z
      - .offset:         266
        .size:           2
        .value_kind:     hidden_remainder_x
      - .offset:         268
        .size:           2
        .value_kind:     hidden_remainder_y
      - .offset:         270
        .size:           2
        .value_kind:     hidden_remainder_z
      - .offset:         288
        .size:           8
        .value_kind:     hidden_global_offset_x
      - .offset:         296
        .size:           8
        .value_kind:     hidden_global_offset_y
      - .offset:         304
        .size:           8
        .value_kind:     hidden_global_offset_z
      - .offset:         312
        .size:           2
        .value_kind:     hidden_grid_dims
      - .offset:         336
        .size:           8
        .value_kind:     hidden_multigrid_sync_arg
      - .offset:         368
        .size:           4
        .value_kind:     hidden_dynamic_lds_size
    .group_segment_fixed_size: 0
    .kernarg_segment_align: 8
    .kernarg_segment_size: 504
    .language:       OpenCL C
    .language_version:
      - 2
      - 0
    .max_flat_workgroup_size: 512
    .name:           _Z4mega6Params
    .private_segment_fixed_size: 0
    .sgpr_count:     108
    .sgpr_spill_count: 204
    .symbol:         _Z4mega6Params.kd
    .uniform_work_group_size: 1
    .uses_dynamic_stack: false
    .vgpr_count:     256
    .vgpr_spill_count: 0
    .wavefront_size: 64
